# store widening (permlane16_swap + dwordx4) extended to E3, E2, G, I, J epilogues
# speedup vs baseline: 1.0375x; 1.0096x over previous
.LBB0_77:
	v_mul_f32_e32 v124, 0xbfb8aa3b, v124
	v_mul_f32_e32 v125, 0xbfb8aa3b, v125
	v_exp_f32_e32 v124, v124
	v_exp_f32_e32 v125, v125
	v_mul_f32_e32 v126, 0xbfb8aa3b, v126
	v_mul_f32_e32 v127, 0xbfb8aa3b, v127
	v_exp_f32_e32 v126, v126
	v_exp_f32_e32 v127, v127
	v_add_f32_e32 v124, 1.0, v124
	v_add_f32_e32 v125, 1.0, v125
	v_rcp_f32_e32 v124, v124
	v_rcp_f32_e32 v125, v125
	v_add_f32_e32 v126, 1.0, v126
	v_add_f32_e32 v127, 1.0, v127
	v_rcp_f32_e32 v126, v126
	v_rcp_f32_e32 v127, v127
	v_pk_mul_f32 v[96:97], v[96:97], v[124:125]
	v_mov_b32_e32 v129, v204
	v_cvt_pk_bf16_f32 v124, v96, v97
	v_pk_mul_f32 v[98:99], v[98:99], v[126:127]
	v_mul_f32_e32 v96, 0xbfb8aa3b, v120
	v_cvt_pk_bf16_f32 v125, v98, v99
	v_exp_f32_e32 v98, v96
	v_mul_f32_e32 v96, 0xbfb8aa3b, v121
	v_exp_f32_e32 v99, v96
	v_mul_f32_e32 v120, 0xbfb8aa3b, v122
	v_add_f32_e32 v98, 1.0, v98
	v_rcp_f32_e32 v98, v98
	v_add_f32_e32 v99, 1.0, v99
	v_rcp_f32_e32 v99, v99
	v_mul_f32_e32 v121, 0xbfb8aa3b, v123
	v_exp_f32_e32 v120, v120
	v_exp_f32_e32 v121, v121
	v_pk_mul_f32 v[88:89], v[88:89], v[98:99]
	v_mul_f32_e32 v98, 0xbfb8aa3b, v116
	v_exp_f32_e32 v98, v98
	v_mul_f32_e32 v99, 0xbfb8aa3b, v117
	v_exp_f32_e32 v99, v99
	v_cvt_pk_bf16_f32 v88, v88, v89
	v_ashrrev_i32_e32 v128, 1, v129
	v_add_f32_e32 v89, 1.0, v98
	v_and_b32_e32 v128, 0xffffffc0, v128
	v_rcp_f32_e32 v98, v89
	v_add_f32_e32 v89, 1.0, v99
	v_mul_f32_e32 v99, 0xbfb8aa3b, v118
	v_add_u32_e32 v128, s19, v128
	v_add_f32_e32 v120, 1.0, v120
	v_add_f32_e32 v121, 1.0, v121
	v_exp_f32_e32 v116, v99
	v_mul_f32_e32 v99, 0xbfb8aa3b, v119
	v_and_b32_e32 v130, 64, v129
	v_and_or_b32 v128, v129, 15, v128
	v_lshrrev_b32_e32 v129, 2, v129
	v_rcp_f32_e32 v120, v120
	v_rcp_f32_e32 v121, v121
	v_exp_f32_e32 v117, v99
	v_and_b32_e32 v129, 12, v129
	v_or3_b32 v130, v130, v129, s18
	v_ashrrev_i32_e32 v129, 31, v128
	v_lshlrev_b64 v[132:133], 11, v[128:129]
	v_ashrrev_i32_e32 v131, 31, v130
	v_rcp_f32_e32 v99, v89
	v_add_f32_e32 v89, 1.0, v116
	v_lshl_add_u64 v[132:133], s[88:89], 0, v[132:133]
	v_lshlrev_b64 v[96:97], 1, v[130:131]
	v_pk_mul_f32 v[90:91], v[90:91], v[120:121]
	v_rcp_f32_e32 v116, v89
	v_add_f32_e32 v89, 1.0, v117
	v_lshl_add_u64 v[122:123], v[132:133], 0, v[96:97]
	v_rcp_f32_e32 v117, v89
	v_cvt_pk_bf16_f32 v89, v90, v91
	v_and_b32_e32 v230, 16, v204
	v_lshrrev_b32_e32 v231, 1, v230
	v_add_u32_e32 v230, v230, v231
	v_mov_b32_e32 v231, v189
	v_mov_b64_e32 v[234:235], v[88:89]
	v_mul_f32_e32 v88, 0xbfb8aa3b, v112
	v_exp_f32_e32 v88, v88
	v_mul_f32_e32 v89, 0xbfb8aa3b, v113
	v_exp_f32_e32 v89, v89
	v_pk_mul_f32 v[80:81], v[80:81], v[98:99]
	v_pk_mul_f32 v[82:83], v[82:83], v[116:117]
	v_cvt_pk_bf16_f32 v80, v80, v81
	v_add_f32_e32 v81, 1.0, v88
	v_rcp_f32_e32 v88, v81
	v_add_f32_e32 v81, 1.0, v89
	v_mul_f32_e32 v89, 0xbfb8aa3b, v114
	v_exp_f32_e32 v90, v89
	v_mul_f32_e32 v89, 0xbfb8aa3b, v115
	v_exp_f32_e32 v91, v89
	v_rcp_f32_e32 v89, v81
	v_add_f32_e32 v81, 1.0, v90
	v_rcp_f32_e32 v90, v81
	v_add_f32_e32 v81, 1.0, v91
	v_rcp_f32_e32 v91, v81
	v_pk_mul_f32 v[72:73], v[72:73], v[88:89]
	v_cvt_pk_bf16_f32 v81, v82, v83
	v_cvt_pk_bf16_f32 v72, v72, v73
	v_pk_mul_f32 v[74:75], v[74:75], v[90:91]
	v_mov_b64_e32 v[236:237], v[80:81]
	v_cvt_pk_bf16_f32 v73, v74, v75
	v_mov_b64_e32 v[238:239], v[72:73]
	s_nop 1
	v_permlane16_swap_b32 v236, v238
	v_permlane16_swap_b32 v237, v239
	v_lshl_add_u64 v[248:249], v[122:123], 0, v[230:231]
	global_store_dwordx4 v[248:249], v[236:239], off offset:64
	s_nop 1
	v_mul_f32_e32 v73, 0xbfb8aa3b, v108
	v_exp_f32_e32 v74, v73
	v_mul_f32_e32 v73, 0xbfb8aa3b, v109
	v_exp_f32_e32 v75, v73
	v_mul_f32_e32 v80, 0xbfb8aa3b, v110
	v_add_f32_e32 v74, 1.0, v74
	v_rcp_f32_e32 v74, v74
	v_add_f32_e32 v75, 1.0, v75
	v_mul_f32_e32 v81, 0xbfb8aa3b, v111
	v_rcp_f32_e32 v75, v75
	v_exp_f32_e32 v80, v80
	v_exp_f32_e32 v81, v81
	v_or_b32_e32 v72, 16, v128
	v_pk_mul_f32 v[64:65], v[64:65], v[74:75]
	v_add_f32_e32 v80, 1.0, v80
	v_add_f32_e32 v81, 1.0, v81
	v_cvt_pk_bf16_f32 v64, v64, v65
	v_mul_f32_e32 v65, 0xbfb8aa3b, v104
	v_rcp_f32_e32 v80, v80
	v_rcp_f32_e32 v81, v81
	v_exp_f32_e32 v74, v65
	v_mul_f32_e32 v65, 0xbfb8aa3b, v105
	v_exp_f32_e32 v75, v65
	v_ashrrev_i32_e32 v73, 31, v72
	v_lshlrev_b64 v[72:73], 11, v[72:73]
	v_lshl_add_u64 v[72:73], s[88:89], 0, v[72:73]
	v_pk_mul_f32 v[66:67], v[66:67], v[80:81]
	v_lshl_add_u64 v[72:73], v[72:73], 0, v[96:97]
	v_cvt_pk_bf16_f32 v65, v66, v67
	v_add_f32_e32 v66, 1.0, v74
	v_add_f32_e32 v67, 1.0, v75
	v_rcp_f32_e32 v66, v66
	v_rcp_f32_e32 v67, v67
	v_mov_b64_e32 v[236:237], v[64:65]
	v_mul_f32_e32 v64, 0xbfb8aa3b, v100
	v_exp_f32_e32 v64, v64
	v_mul_f32_e32 v65, 0xbfb8aa3b, v101
	v_mul_f32_e32 v74, 0xbfb8aa3b, v106
	v_mul_f32_e32 v75, 0xbfb8aa3b, v107
	v_exp_f32_e32 v65, v65
	v_exp_f32_e32 v74, v74
	v_exp_f32_e32 v75, v75
	v_pk_mul_f32 v[60:61], v[60:61], v[66:67]
	s_add_i32 s0, s0, s96
	v_cvt_pk_bf16_f32 v60, v60, v61
	v_add_f32_e32 v61, 1.0, v64
	v_rcp_f32_e32 v64, v61
	v_add_f32_e32 v61, 1.0, v65
	v_mul_f32_e32 v65, 0xbfb8aa3b, v102
	v_add_f32_e32 v74, 1.0, v74
	v_add_f32_e32 v75, 1.0, v75
	v_exp_f32_e32 v66, v65
	v_mul_f32_e32 v65, 0xbfb8aa3b, v103
	v_rcp_f32_e32 v74, v74
	v_rcp_f32_e32 v75, v75
	v_exp_f32_e32 v67, v65
	v_rcp_f32_e32 v65, v61
	v_add_f32_e32 v61, 1.0, v66
	v_pk_mul_f32 v[62:63], v[62:63], v[74:75]
	v_rcp_f32_e32 v66, v61
	v_add_f32_e32 v61, 1.0, v67
	v_rcp_f32_e32 v67, v61
	v_cvt_pk_bf16_f32 v61, v62, v63
	v_mov_b64_e32 v[238:239], v[60:61]
	s_nop 1
	v_permlane16_swap_b32 v236, v238
	v_permlane16_swap_b32 v237, v239
	v_lshl_add_u64 v[248:249], v[72:73], 0, v[230:231]
	global_store_dwordx4 v[248:249], v[236:239], off
	s_nop 1
	v_mul_f32_e32 v60, 0xbfb8aa3b, v92
	v_exp_f32_e32 v60, v60
	v_mul_f32_e32 v61, 0xbfb8aa3b, v93
	v_exp_f32_e32 v61, v61
	v_pk_mul_f32 v[52:53], v[52:53], v[64:65]
	v_pk_mul_f32 v[54:55], v[54:55], v[66:67]
	v_cvt_pk_bf16_f32 v52, v52, v53
	v_add_f32_e32 v53, 1.0, v60
	v_rcp_f32_e32 v60, v53
	v_add_f32_e32 v53, 1.0, v61
	v_mul_f32_e32 v61, 0xbfb8aa3b, v94
	v_exp_f32_e32 v62, v61
	v_mul_f32_e32 v61, 0xbfb8aa3b, v95
	v_exp_f32_e32 v63, v61
	v_rcp_f32_e32 v61, v53
	v_add_f32_e32 v53, 1.0, v62
	v_rcp_f32_e32 v62, v53
	v_add_f32_e32 v53, 1.0, v63
	v_rcp_f32_e32 v63, v53
	v_pk_mul_f32 v[44:45], v[44:45], v[60:61]
	v_cvt_pk_bf16_f32 v53, v54, v55
	v_cvt_pk_bf16_f32 v44, v44, v45
	v_pk_mul_f32 v[46:47], v[46:47], v[62:63]
	v_mov_b64_e32 v[236:237], v[52:53]
	v_cvt_pk_bf16_f32 v45, v46, v47
	v_mov_b64_e32 v[238:239], v[44:45]
	s_nop 1
	v_permlane16_swap_b32 v236, v238
	v_permlane16_swap_b32 v237, v239
	v_lshl_add_u64 v[248:249], v[72:73], 0, v[230:231]
	global_store_dwordx4 v[248:249], v[236:239], off offset:64
	s_nop 1
	v_mul_f32_e32 v45, 0xbfb8aa3b, v84
	v_exp_f32_e32 v46, v45
	v_mul_f32_e32 v45, 0xbfb8aa3b, v85
	v_exp_f32_e32 v47, v45
	v_mul_f32_e32 v52, 0xbfb8aa3b, v86
	v_add_f32_e32 v46, 1.0, v46
	v_rcp_f32_e32 v46, v46
	v_add_f32_e32 v47, 1.0, v47
	v_mul_f32_e32 v53, 0xbfb8aa3b, v87
	v_rcp_f32_e32 v47, v47
	v_exp_f32_e32 v52, v52
	v_exp_f32_e32 v53, v53
	v_or_b32_e32 v44, 32, v128
	v_pk_mul_f32 v[36:37], v[36:37], v[46:47]
	v_add_f32_e32 v52, 1.0, v52
	v_add_f32_e32 v53, 1.0, v53
	v_cvt_pk_bf16_f32 v36, v36, v37
	v_mul_f32_e32 v37, 0xbfb8aa3b, v76
	v_rcp_f32_e32 v52, v52
	v_rcp_f32_e32 v53, v53
	v_exp_f32_e32 v46, v37
	v_mul_f32_e32 v37, 0xbfb8aa3b, v77
	v_exp_f32_e32 v47, v37
	v_ashrrev_i32_e32 v45, 31, v44
	v_lshlrev_b64 v[44:45], 11, v[44:45]
	v_lshl_add_u64 v[44:45], s[88:89], 0, v[44:45]
	v_pk_mul_f32 v[38:39], v[38:39], v[52:53]
	v_lshl_add_u64 v[44:45], v[44:45], 0, v[96:97]
	v_cvt_pk_bf16_f32 v37, v38, v39
	v_add_f32_e32 v38, 1.0, v46
	v_add_f32_e32 v39, 1.0, v47
	v_rcp_f32_e32 v38, v38
	v_rcp_f32_e32 v39, v39
	v_mov_b64_e32 v[236:237], v[36:37]
	v_mul_f32_e32 v36, 0xbfb8aa3b, v68
	v_exp_f32_e32 v36, v36
	v_mul_f32_e32 v37, 0xbfb8aa3b, v69
	v_mul_f32_e32 v46, 0xbfb8aa3b, v78
	v_mul_f32_e32 v47, 0xbfb8aa3b, v79
	v_exp_f32_e32 v37, v37
	v_exp_f32_e32 v46, v46
	v_exp_f32_e32 v47, v47
	v_pk_mul_f32 v[28:29], v[28:29], v[38:39]
	s_cmpk_gt_i32 s0, 0x3ff
	v_cvt_pk_bf16_f32 v28, v28, v29
	v_add_f32_e32 v29, 1.0, v36
	v_rcp_f32_e32 v36, v29
	v_add_f32_e32 v29, 1.0, v37
	v_mul_f32_e32 v37, 0xbfb8aa3b, v70
	v_add_f32_e32 v46, 1.0, v46
	v_add_f32_e32 v47, 1.0, v47
	v_exp_f32_e32 v38, v37
	v_mul_f32_e32 v37, 0xbfb8aa3b, v71
	v_rcp_f32_e32 v46, v46
	v_rcp_f32_e32 v47, v47
	v_exp_f32_e32 v39, v37
	v_rcp_f32_e32 v37, v29
	v_add_f32_e32 v29, 1.0, v38
	v_pk_mul_f32 v[30:31], v[30:31], v[46:47]
	v_rcp_f32_e32 v38, v29
	v_add_f32_e32 v29, 1.0, v39
	v_rcp_f32_e32 v39, v29
	v_cvt_pk_bf16_f32 v29, v30, v31
	v_mov_b64_e32 v[238:239], v[28:29]
	s_nop 1
	v_permlane16_swap_b32 v236, v238
	v_permlane16_swap_b32 v237, v239
	v_lshl_add_u64 v[248:249], v[44:45], 0, v[230:231]
	global_store_dwordx4 v[248:249], v[236:239], off
	s_nop 1
	v_mul_f32_e32 v28, 0xbfb8aa3b, v56
	v_exp_f32_e32 v28, v28
	v_mul_f32_e32 v29, 0xbfb8aa3b, v57
	v_exp_f32_e32 v29, v29
	v_pk_mul_f32 v[20:21], v[20:21], v[36:37]
	v_pk_mul_f32 v[22:23], v[22:23], v[38:39]
	v_cvt_pk_bf16_f32 v20, v20, v21
	v_add_f32_e32 v21, 1.0, v28
	v_rcp_f32_e32 v28, v21
	v_add_f32_e32 v21, 1.0, v29
	v_mul_f32_e32 v29, 0xbfb8aa3b, v58
	v_exp_f32_e32 v30, v29
	v_mul_f32_e32 v29, 0xbfb8aa3b, v59
	v_exp_f32_e32 v31, v29
	v_rcp_f32_e32 v29, v21
	v_add_f32_e32 v21, 1.0, v30
	v_rcp_f32_e32 v30, v21
	v_add_f32_e32 v21, 1.0, v31
	v_rcp_f32_e32 v31, v21
	v_pk_mul_f32 v[16:17], v[16:17], v[28:29]
	v_cvt_pk_bf16_f32 v21, v22, v23
	v_cvt_pk_bf16_f32 v16, v16, v17
	v_pk_mul_f32 v[18:19], v[18:19], v[30:31]
	v_mov_b64_e32 v[236:237], v[20:21]
	v_cvt_pk_bf16_f32 v17, v18, v19
	v_mov_b64_e32 v[238:239], v[16:17]
	s_nop 1
	v_permlane16_swap_b32 v236, v238
	v_permlane16_swap_b32 v237, v239
	v_lshl_add_u64 v[248:249], v[44:45], 0, v[230:231]
	global_store_dwordx4 v[248:249], v[236:239], off offset:64
	s_nop 1
	v_mul_f32_e32 v17, 0xbfb8aa3b, v48
	v_exp_f32_e32 v18, v17
	v_mul_f32_e32 v17, 0xbfb8aa3b, v49
	v_exp_f32_e32 v19, v17
	v_mul_f32_e32 v20, 0xbfb8aa3b, v50
	v_add_f32_e32 v18, 1.0, v18
	v_rcp_f32_e32 v18, v18
	v_add_f32_e32 v19, 1.0, v19
	v_mul_f32_e32 v21, 0xbfb8aa3b, v51
	v_rcp_f32_e32 v19, v19
	v_exp_f32_e32 v20, v20
	v_exp_f32_e32 v21, v21
	v_or_b32_e32 v16, 48, v128
	v_pk_mul_f32 v[12:13], v[12:13], v[18:19]
	v_add_f32_e32 v20, 1.0, v20
	v_add_f32_e32 v21, 1.0, v21
	v_cvt_pk_bf16_f32 v12, v12, v13
	v_mul_f32_e32 v13, 0xbfb8aa3b, v40
	v_rcp_f32_e32 v20, v20
	v_rcp_f32_e32 v21, v21
	v_exp_f32_e32 v18, v13
	v_mul_f32_e32 v13, 0xbfb8aa3b, v41
	v_exp_f32_e32 v19, v13
	v_ashrrev_i32_e32 v17, 31, v16
	v_lshlrev_b64 v[16:17], 11, v[16:17]
	v_lshl_add_u64 v[16:17], s[88:89], 0, v[16:17]
	v_pk_mul_f32 v[14:15], v[14:15], v[20:21]
	v_lshl_add_u64 v[16:17], v[16:17], 0, v[96:97]
	v_cvt_pk_bf16_f32 v13, v14, v15
	v_add_f32_e32 v14, 1.0, v18
	v_add_f32_e32 v15, 1.0, v19
	v_rcp_f32_e32 v14, v14
	v_rcp_f32_e32 v15, v15
	v_mov_b64_e32 v[236:237], v[12:13]
	v_mul_f32_e32 v12, 0xbfb8aa3b, v32
	v_exp_f32_e32 v12, v12
	v_mul_f32_e32 v13, 0xbfb8aa3b, v33
	v_mul_f32_e32 v18, 0xbfb8aa3b, v42
	v_mul_f32_e32 v19, 0xbfb8aa3b, v43
	v_exp_f32_e32 v13, v13
	v_exp_f32_e32 v18, v18
	v_exp_f32_e32 v19, v19
	v_pk_mul_f32 v[8:9], v[8:9], v[14:15]
	v_mov_b64_e32 v[232:233], v[124:125]
	s_nop 1
	v_permlane16_swap_b32 v232, v234
	v_permlane16_swap_b32 v233, v235
	v_lshl_add_u64 v[248:249], v[122:123], 0, v[230:231]
	global_store_dwordx4 v[248:249], v[232:235], off
	s_nop 1
	v_cvt_pk_bf16_f32 v8, v8, v9
	v_add_f32_e32 v9, 1.0, v12
	v_rcp_f32_e32 v12, v9
	v_add_f32_e32 v9, 1.0, v13
	v_mul_f32_e32 v13, 0xbfb8aa3b, v34
	v_add_f32_e32 v18, 1.0, v18
	v_add_f32_e32 v19, 1.0, v19
	v_exp_f32_e32 v14, v13
	v_mul_f32_e32 v13, 0xbfb8aa3b, v35
	v_rcp_f32_e32 v18, v18
	v_rcp_f32_e32 v19, v19
	v_exp_f32_e32 v15, v13
	v_rcp_f32_e32 v13, v9
	v_add_f32_e32 v9, 1.0, v14
	v_pk_mul_f32 v[10:11], v[10:11], v[18:19]
	v_rcp_f32_e32 v14, v9
	v_add_f32_e32 v9, 1.0, v15
	v_rcp_f32_e32 v15, v9
	v_cvt_pk_bf16_f32 v9, v10, v11
	v_mov_b64_e32 v[238:239], v[8:9]
	s_nop 1
	v_permlane16_swap_b32 v236, v238
	v_permlane16_swap_b32 v237, v239
	v_lshl_add_u64 v[248:249], v[16:17], 0, v[230:231]
	global_store_dwordx4 v[248:249], v[236:239], off
	s_nop 1
	v_mul_f32_e32 v8, 0xbfb8aa3b, v24
	v_exp_f32_e32 v8, v8
	v_mul_f32_e32 v9, 0xbfb8aa3b, v25
	v_exp_f32_e32 v9, v9
	v_pk_mul_f32 v[4:5], v[4:5], v[12:13]
	v_pk_mul_f32 v[6:7], v[6:7], v[14:15]
	v_cvt_pk_bf16_f32 v4, v4, v5
	v_add_f32_e32 v5, 1.0, v8
	v_rcp_f32_e32 v8, v5
	v_add_f32_e32 v5, 1.0, v9
	v_mul_f32_e32 v9, 0xbfb8aa3b, v26
	v_exp_f32_e32 v10, v9
	v_mul_f32_e32 v9, 0xbfb8aa3b, v27
	v_exp_f32_e32 v11, v9
	v_rcp_f32_e32 v9, v5
	v_add_f32_e32 v5, 1.0, v10
	v_rcp_f32_e32 v10, v5
	v_add_f32_e32 v5, 1.0, v11
	v_rcp_f32_e32 v11, v5
	v_pk_mul_f32 v[0:1], v[0:1], v[8:9]
	v_cvt_pk_bf16_f32 v5, v6, v7
	v_cvt_pk_bf16_f32 v0, v0, v1
	v_pk_mul_f32 v[2:3], v[2:3], v[10:11]
	v_mov_b64_e32 v[232:233], v[4:5]
	v_cvt_pk_bf16_f32 v1, v2, v3
	v_mov_b64_e32 v[234:235], v[0:1]
	s_nop 1
	v_permlane16_swap_b32 v232, v234
	v_permlane16_swap_b32 v233, v235
	v_lshl_add_u64 v[248:249], v[16:17], 0, v[230:231]
	global_store_dwordx4 v[248:249], v[232:235], off offset:64
	s_nop 1
	s_cbranch_scc1 .LBB0_91

.LBB0_110:
	s_add_u32 s12, s10, 0x100
	s_addc_u32 s13, s11, 0
	s_add_i32 s37, 0, 0x10000
	v_add_u32_e32 v139, s37, v137
	ds_read_b128 v[140:143], v139
	ds_read_b128 v[144:147], v139 offset:1024
	ds_read_b128 v[148:151], v139 offset:2048
	ds_read_b128 v[152:155], v139 offset:3072
	s_cmp_eq_u32 s36, 40
	s_cselect_b32 s17, s9, s13
	s_cselect_b32 s16, s8, s12
	s_cselect_b32 s15, s5, s35
	s_cselect_b32 s14, s4, s34
	v_lshl_add_u64 v[190:191], s[10:11], 0, v[132:133]
	s_add_i32 m0, s22, 0xc000
	ds_read_b128 v[156:159], v138
	ds_read_b128 v[160:163], v138 offset:1024
	ds_read_b128 v[164:167], v138 offset:2048
	ds_read_b128 v[168:171], v138 offset:3072
	ds_read_b128 v[172:175], v138 offset:4096
	ds_read_b128 v[176:179], v138 offset:5120
	ds_read_b128 v[180:183], v138 offset:6144
	ds_read_b128 v[184:187], v138 offset:7168
	global_load_lds_dwordx4 v[190:191], off
	v_lshl_add_u64 v[190:191], s[10:11], 0, v[134:135]
	s_add_i32 m0, s22, 0xe000
	s_nop 0
	global_load_lds_dwordx4 v[190:191], off
	s_waitcnt lgkmcnt(8)
	s_barrier
	s_waitcnt lgkmcnt(0)
	s_setprio 1
	s_waitcnt lgkmcnt(0)
	v_mfma_f32_16x16x32_bf16 v[124:127], v[140:143], v[156:159], v[124:127]
	v_mfma_f32_16x16x32_bf16 v[120:123], v[148:151], v[156:159], v[120:123]
	v_mfma_f32_16x16x32_bf16 v[116:119], v[140:143], v[164:167], v[116:119]
	v_mfma_f32_16x16x32_bf16 v[108:111], v[148:151], v[164:167], v[108:111]
	v_mfma_f32_16x16x32_bf16 v[100:103], v[140:143], v[172:175], v[100:103]
	v_mfma_f32_16x16x32_bf16 v[92:95], v[148:151], v[172:175], v[92:95]
	v_mfma_f32_16x16x32_bf16 v[84:87], v[140:143], v[180:183], v[84:87]
	v_mfma_f32_16x16x32_bf16 v[76:79], v[148:151], v[180:183], v[76:79]
	v_mfma_f32_16x16x32_bf16 v[124:127], v[144:147], v[160:163], v[124:127]
	v_mfma_f32_16x16x32_bf16 v[120:123], v[152:155], v[160:163], v[120:123]
	v_mfma_f32_16x16x32_bf16 v[116:119], v[144:147], v[168:171], v[116:119]
	v_mfma_f32_16x16x32_bf16 v[108:111], v[152:155], v[168:171], v[108:111]
	v_mfma_f32_16x16x32_bf16 v[100:103], v[144:147], v[176:179], v[100:103]
	v_mfma_f32_16x16x32_bf16 v[92:95], v[152:155], v[176:179], v[92:95]
	v_mfma_f32_16x16x32_bf16 v[84:87], v[144:147], v[184:187], v[84:87]
	v_mfma_f32_16x16x32_bf16 v[76:79], v[152:155], v[184:187], v[76:79]
	s_setprio 0
	s_barrier
	s_add_i32 s38, 0, 0x14000
	s_add_i32 s10, s37, s21
	v_add_u32_e32 v139, s38, v137
	v_lshl_add_u64 v[202:203], s[14:15], 0, v[130:131]
	s_mov_b32 m0, s10
	ds_read_b128 v[190:193], v139
	ds_read_b128 v[194:197], v139 offset:1024
	ds_read_b128 v[198:201], v139 offset:2048
	ds_read_b128 v[216:219], v139 offset:3072
	global_load_lds_dwordx4 v[202:203], off
	v_lshl_add_u64 v[220:221], s[14:15], 0, v[128:129]
	s_add_i32 m0, s10, 0x2000
	s_nop 0
	global_load_lds_dwordx4 v[220:221], off
	s_barrier
	s_waitcnt lgkmcnt(0)
	s_setprio 1
	s_waitcnt lgkmcnt(0)
	v_mfma_f32_16x16x32_bf16 v[112:115], v[190:193], v[156:159], v[112:115]
	v_mfma_f32_16x16x32_bf16 v[104:107], v[198:201], v[156:159], v[104:107]
	v_mfma_f32_16x16x32_bf16 v[96:99], v[190:193], v[164:167], v[96:99]
	v_mfma_f32_16x16x32_bf16 v[88:91], v[198:201], v[164:167], v[88:91]
	v_mfma_f32_16x16x32_bf16 v[80:83], v[190:193], v[172:175], v[80:83]
	v_mfma_f32_16x16x32_bf16 v[72:75], v[198:201], v[172:175], v[72:75]
	v_mfma_f32_16x16x32_bf16 v[68:71], v[190:193], v[180:183], v[68:71]
	v_mfma_f32_16x16x32_bf16 v[64:67], v[198:201], v[180:183], v[64:67]
	v_mfma_f32_16x16x32_bf16 v[112:115], v[194:197], v[160:163], v[112:115]
	v_mfma_f32_16x16x32_bf16 v[104:107], v[216:219], v[160:163], v[104:107]
	v_mfma_f32_16x16x32_bf16 v[96:99], v[194:197], v[168:171], v[96:99]
	v_mfma_f32_16x16x32_bf16 v[88:91], v[216:219], v[168:171], v[88:91]
	v_mfma_f32_16x16x32_bf16 v[80:83], v[194:197], v[176:179], v[80:83]
	v_mfma_f32_16x16x32_bf16 v[72:75], v[216:219], v[176:179], v[72:75]
	v_mfma_f32_16x16x32_bf16 v[68:71], v[194:197], v[184:187], v[68:71]
	v_mfma_f32_16x16x32_bf16 v[64:67], v[216:219], v[184:187], v[64:67]
	s_setprio 0
	s_mov_b32 m0, s22
	v_lshl_add_u64 v[222:223], s[16:17], 0, v[130:131]
	s_barrier
	ds_read_b128 v[156:159], v138 offset:16384
	ds_read_b128 v[160:163], v138 offset:17408
	ds_read_b128 v[164:167], v138 offset:18432
	ds_read_b128 v[168:171], v138 offset:19456
	ds_read_b128 v[172:175], v138 offset:20480
	ds_read_b128 v[176:179], v138 offset:21504
	ds_read_b128 v[180:183], v138 offset:22528
	ds_read_b128 v[184:187], v138 offset:23552
	global_load_lds_dwordx4 v[222:223], off
	v_lshl_add_u64 v[224:225], s[16:17], 0, v[128:129]
	s_mov_b32 m0, s23
	s_nop 0
	global_load_lds_dwordx4 v[224:225], off
	s_barrier
	s_waitcnt lgkmcnt(0)
	s_setprio 1
	s_waitcnt lgkmcnt(0)
	v_mfma_f32_16x16x32_bf16 v[60:63], v[140:143], v[156:159], v[60:63]
	v_mfma_f32_16x16x32_bf16 v[56:59], v[148:151], v[156:159], v[56:59]
	v_mfma_f32_16x16x32_bf16 v[52:55], v[140:143], v[164:167], v[52:55]
	v_mfma_f32_16x16x32_bf16 v[44:47], v[148:151], v[164:167], v[44:47]
	v_mfma_f32_16x16x32_bf16 v[36:39], v[140:143], v[172:175], v[36:39]
	v_mfma_f32_16x16x32_bf16 v[28:31], v[148:151], v[172:175], v[28:31]
	v_mfma_f32_16x16x32_bf16 v[20:23], v[140:143], v[180:183], v[20:23]
	v_mfma_f32_16x16x32_bf16 v[12:15], v[148:151], v[180:183], v[12:15]
	v_mfma_f32_16x16x32_bf16 v[60:63], v[144:147], v[160:163], v[60:63]
	v_mfma_f32_16x16x32_bf16 v[56:59], v[152:155], v[160:163], v[56:59]
	v_mfma_f32_16x16x32_bf16 v[52:55], v[144:147], v[168:171], v[52:55]
	v_mfma_f32_16x16x32_bf16 v[44:47], v[152:155], v[168:171], v[44:47]
	v_mfma_f32_16x16x32_bf16 v[36:39], v[144:147], v[176:179], v[36:39]
	v_mfma_f32_16x16x32_bf16 v[28:31], v[152:155], v[176:179], v[28:31]
	v_mfma_f32_16x16x32_bf16 v[20:23], v[144:147], v[184:187], v[20:23]
	v_mfma_f32_16x16x32_bf16 v[12:15], v[152:155], v[184:187], v[12:15]
	s_setprio 0
	s_barrier
	s_add_u32 s10, s14, 0xb0000
	s_addc_u32 s11, s15, 0
	s_add_i32 s37, s38, s21
	v_lshl_add_u64 v[140:141], s[10:11], 0, v[130:131]
	s_mov_b32 m0, s37
	s_nop 0
	global_load_lds_dwordx4 v[140:141], off
	v_lshl_add_u64 v[140:141], s[10:11], 0, v[128:129]
	s_add_i32 m0, s37, 0x2000
	s_nop 0
	global_load_lds_dwordx4 v[140:141], off
	s_waitcnt vmcnt(6)
	s_barrier
	s_setprio 1
	v_mfma_f32_16x16x32_bf16 v[48:51], v[190:193], v[156:159], v[48:51]
	v_mfma_f32_16x16x32_bf16 v[40:43], v[198:201], v[156:159], v[40:43]
	v_mfma_f32_16x16x32_bf16 v[32:35], v[190:193], v[164:167], v[32:35]
	v_mfma_f32_16x16x32_bf16 v[24:27], v[198:201], v[164:167], v[24:27]
	v_mfma_f32_16x16x32_bf16 v[16:19], v[190:193], v[172:175], v[16:19]
	v_mfma_f32_16x16x32_bf16 v[8:11], v[198:201], v[172:175], v[8:11]
	v_mfma_f32_16x16x32_bf16 v[4:7], v[190:193], v[180:183], v[4:7]
	v_mfma_f32_16x16x32_bf16 v[0:3], v[198:201], v[180:183], v[0:3]
	v_mfma_f32_16x16x32_bf16 v[48:51], v[194:197], v[160:163], v[48:51]
	v_mfma_f32_16x16x32_bf16 v[40:43], v[216:219], v[160:163], v[40:43]
	v_mfma_f32_16x16x32_bf16 v[32:35], v[194:197], v[168:171], v[32:35]
	v_mfma_f32_16x16x32_bf16 v[24:27], v[216:219], v[168:171], v[24:27]
	v_mfma_f32_16x16x32_bf16 v[16:19], v[194:197], v[176:179], v[16:19]
	v_mfma_f32_16x16x32_bf16 v[8:11], v[216:219], v[176:179], v[8:11]
	v_mfma_f32_16x16x32_bf16 v[4:7], v[194:197], v[184:187], v[4:7]
	v_mfma_f32_16x16x32_bf16 v[0:3], v[216:219], v[184:187], v[0:3]
	s_setprio 0
	s_add_i32 s37, 0, 0x18000
	v_add_u32_e32 v139, s37, v137
	s_barrier
	ds_read_b128 v[140:143], v139
	ds_read_b128 v[144:147], v139 offset:1024
	ds_read_b128 v[148:151], v139 offset:2048
	ds_read_b128 v[152:155], v139 offset:3072
	s_add_u32 s10, s16, 0xb0000
	s_addc_u32 s11, s17, 0
	s_mov_b32 m0, s24
	v_lshl_add_u64 v[190:191], s[10:11], 0, v[130:131]
	ds_read_b128 v[156:159], v138 offset:32768
	ds_read_b128 v[160:163], v138 offset:33792
	ds_read_b128 v[164:167], v138 offset:34816
	ds_read_b128 v[168:171], v138 offset:35840
	ds_read_b128 v[172:175], v138 offset:36864
	ds_read_b128 v[176:179], v138 offset:37888
	ds_read_b128 v[180:183], v138 offset:38912
	ds_read_b128 v[184:187], v138 offset:39936
	global_load_lds_dwordx4 v[190:191], off
	v_lshl_add_u64 v[190:191], s[10:11], 0, v[128:129]
	s_mov_b32 m0, s25
	s_nop 0
	global_load_lds_dwordx4 v[190:191], off
	s_waitcnt lgkmcnt(8)
	s_barrier
	s_waitcnt lgkmcnt(0)
	s_setprio 1
	s_waitcnt lgkmcnt(0)
	v_mfma_f32_16x16x32_bf16 v[124:127], v[140:143], v[156:159], v[124:127]
	v_mfma_f32_16x16x32_bf16 v[120:123], v[148:151], v[156:159], v[120:123]
	v_mfma_f32_16x16x32_bf16 v[116:119], v[140:143], v[164:167], v[116:119]
	v_mfma_f32_16x16x32_bf16 v[108:111], v[148:151], v[164:167], v[108:111]
	v_mfma_f32_16x16x32_bf16 v[100:103], v[140:143], v[172:175], v[100:103]
	v_mfma_f32_16x16x32_bf16 v[92:95], v[148:151], v[172:175], v[92:95]
	v_mfma_f32_16x16x32_bf16 v[84:87], v[140:143], v[180:183], v[84:87]
	v_mfma_f32_16x16x32_bf16 v[76:79], v[148:151], v[180:183], v[76:79]
	v_mfma_f32_16x16x32_bf16 v[124:127], v[144:147], v[160:163], v[124:127]
	v_mfma_f32_16x16x32_bf16 v[120:123], v[152:155], v[160:163], v[120:123]
	v_mfma_f32_16x16x32_bf16 v[116:119], v[144:147], v[168:171], v[116:119]
	v_mfma_f32_16x16x32_bf16 v[108:111], v[152:155], v[168:171], v[108:111]
	v_mfma_f32_16x16x32_bf16 v[100:103], v[144:147], v[176:179], v[100:103]
	v_mfma_f32_16x16x32_bf16 v[92:95], v[152:155], v[176:179], v[92:95]
	v_mfma_f32_16x16x32_bf16 v[84:87], v[144:147], v[184:187], v[84:87]
	v_mfma_f32_16x16x32_bf16 v[76:79], v[152:155], v[184:187], v[76:79]
	s_setprio 0
	s_barrier
	s_add_i32 s16, 0, 0x1c000
	s_add_i32 s10, s37, s21
	v_add_u32_e32 v139, s16, v137
	v_lshl_add_u64 v[202:203], v[202:203], 0, s[92:93]
	s_mov_b32 m0, s10
	ds_read_b128 v[190:193], v139
	ds_read_b128 v[194:197], v139 offset:1024
	ds_read_b128 v[198:201], v139 offset:2048
	ds_read_b128 v[216:219], v139 offset:3072
	global_load_lds_dwordx4 v[202:203], off
	v_lshl_add_u64 v[202:203], v[220:221], 0, s[92:93]
	s_add_i32 m0, s10, 0x2000
	s_nop 0
	global_load_lds_dwordx4 v[202:203], off
	s_barrier
	s_waitcnt lgkmcnt(0)
	s_setprio 1
	s_waitcnt lgkmcnt(0)
	v_mfma_f32_16x16x32_bf16 v[112:115], v[190:193], v[156:159], v[112:115]
	v_mfma_f32_16x16x32_bf16 v[104:107], v[198:201], v[156:159], v[104:107]
	v_mfma_f32_16x16x32_bf16 v[96:99], v[190:193], v[164:167], v[96:99]
	v_mfma_f32_16x16x32_bf16 v[88:91], v[198:201], v[164:167], v[88:91]
	v_mfma_f32_16x16x32_bf16 v[80:83], v[190:193], v[172:175], v[80:83]
	v_mfma_f32_16x16x32_bf16 v[72:75], v[198:201], v[172:175], v[72:75]
	v_mfma_f32_16x16x32_bf16 v[68:71], v[190:193], v[180:183], v[68:71]
	v_mfma_f32_16x16x32_bf16 v[64:67], v[198:201], v[180:183], v[64:67]
	v_mfma_f32_16x16x32_bf16 v[112:115], v[194:197], v[160:163], v[112:115]
	v_mfma_f32_16x16x32_bf16 v[104:107], v[216:219], v[160:163], v[104:107]
	v_mfma_f32_16x16x32_bf16 v[96:99], v[194:197], v[168:171], v[96:99]
	v_mfma_f32_16x16x32_bf16 v[88:91], v[216:219], v[168:171], v[88:91]
	v_mfma_f32_16x16x32_bf16 v[80:83], v[194:197], v[176:179], v[80:83]
	v_mfma_f32_16x16x32_bf16 v[72:75], v[216:219], v[176:179], v[72:75]
	v_mfma_f32_16x16x32_bf16 v[68:71], v[194:197], v[184:187], v[68:71]
	v_mfma_f32_16x16x32_bf16 v[64:67], v[216:219], v[184:187], v[64:67]
	s_setprio 0
	s_mov_b32 m0, s26
	v_lshl_add_u64 v[202:203], v[222:223], 0, s[92:93]
	s_barrier
	ds_read_b128 v[156:159], v138 offset:49152
	ds_read_b128 v[160:163], v138 offset:50176
	ds_read_b128 v[164:167], v138 offset:51200
	ds_read_b128 v[168:171], v138 offset:52224
	ds_read_b128 v[172:175], v138 offset:53248
	ds_read_b128 v[176:179], v138 offset:54272
	ds_read_b128 v[180:183], v138 offset:55296
	ds_read_b128 v[184:187], v138 offset:56320
	global_load_lds_dwordx4 v[202:203], off
	v_lshl_add_u64 v[202:203], v[224:225], 0, s[92:93]
	s_mov_b32 m0, s27
	s_nop 0
	global_load_lds_dwordx4 v[202:203], off
	s_barrier
	s_waitcnt lgkmcnt(0)
	s_setprio 1
	s_waitcnt lgkmcnt(0)
	v_mfma_f32_16x16x32_bf16 v[60:63], v[140:143], v[156:159], v[60:63]
	v_mfma_f32_16x16x32_bf16 v[56:59], v[148:151], v[156:159], v[56:59]
	v_mfma_f32_16x16x32_bf16 v[52:55], v[140:143], v[164:167], v[52:55]
	v_mfma_f32_16x16x32_bf16 v[44:47], v[148:151], v[164:167], v[44:47]
	v_mfma_f32_16x16x32_bf16 v[36:39], v[140:143], v[172:175], v[36:39]
	v_mfma_f32_16x16x32_bf16 v[28:31], v[148:151], v[172:175], v[28:31]
	v_mfma_f32_16x16x32_bf16 v[20:23], v[140:143], v[180:183], v[20:23]
	v_mfma_f32_16x16x32_bf16 v[12:15], v[148:151], v[180:183], v[12:15]
	v_mfma_f32_16x16x32_bf16 v[60:63], v[144:147], v[160:163], v[60:63]
	v_mfma_f32_16x16x32_bf16 v[56:59], v[152:155], v[160:163], v[56:59]
	v_mfma_f32_16x16x32_bf16 v[52:55], v[144:147], v[168:171], v[52:55]
	v_mfma_f32_16x16x32_bf16 v[44:47], v[152:155], v[168:171], v[44:47]
	v_mfma_f32_16x16x32_bf16 v[36:39], v[144:147], v[176:179], v[36:39]
	v_mfma_f32_16x16x32_bf16 v[28:31], v[152:155], v[176:179], v[28:31]
	v_mfma_f32_16x16x32_bf16 v[20:23], v[144:147], v[184:187], v[20:23]
	v_mfma_f32_16x16x32_bf16 v[12:15], v[152:155], v[184:187], v[12:15]
	s_setprio 0
	s_barrier
	s_add_u32 s10, s14, 0xb0080
	s_addc_u32 s11, s15, 0
	s_add_i32 s14, s16, s21
	v_lshl_add_u64 v[140:141], s[10:11], 0, v[130:131]
	s_mov_b32 m0, s14
	s_nop 0
	global_load_lds_dwordx4 v[140:141], off
	v_lshl_add_u64 v[140:141], s[10:11], 0, v[128:129]
	s_add_i32 m0, s14, 0x2000
	s_nop 0
	global_load_lds_dwordx4 v[140:141], off
	s_waitcnt vmcnt(6)
	s_barrier
	s_setprio 1
	v_mfma_f32_16x16x32_bf16 v[48:51], v[190:193], v[156:159], v[48:51]
	v_mfma_f32_16x16x32_bf16 v[40:43], v[198:201], v[156:159], v[40:43]
	v_mfma_f32_16x16x32_bf16 v[32:35], v[190:193], v[164:167], v[32:35]
	v_mfma_f32_16x16x32_bf16 v[24:27], v[198:201], v[164:167], v[24:27]
	v_mfma_f32_16x16x32_bf16 v[16:19], v[190:193], v[172:175], v[16:19]
	v_mfma_f32_16x16x32_bf16 v[8:11], v[198:201], v[172:175], v[8:11]
	v_mfma_f32_16x16x32_bf16 v[4:7], v[190:193], v[180:183], v[4:7]
	v_mfma_f32_16x16x32_bf16 v[0:3], v[198:201], v[180:183], v[0:3]
	v_mfma_f32_16x16x32_bf16 v[48:51], v[194:197], v[160:163], v[48:51]
	v_mfma_f32_16x16x32_bf16 v[40:43], v[216:219], v[160:163], v[40:43]
	v_mfma_f32_16x16x32_bf16 v[32:35], v[194:197], v[168:171], v[32:35]
	v_mfma_f32_16x16x32_bf16 v[24:27], v[216:219], v[168:171], v[24:27]
	v_mfma_f32_16x16x32_bf16 v[16:19], v[194:197], v[176:179], v[16:19]
	v_mfma_f32_16x16x32_bf16 v[8:11], v[216:219], v[176:179], v[8:11]
	v_mfma_f32_16x16x32_bf16 v[4:7], v[194:197], v[184:187], v[4:7]
	v_mfma_f32_16x16x32_bf16 v[0:3], v[216:219], v[184:187], v[0:3]
	s_setprio 0
	s_add_i32 s36, s36, 2
	s_add_u32 s34, s34, 0x100
	s_addc_u32 s35, s35, 0
	s_cmp_gt_u32 s36, 41
	s_mov_b64 s[10:11], s[12:13]
	s_barrier
	s_cbranch_scc0 .LBB0_110
	v_lshl_add_u32 v140, s33, 8, v136
	s_lshl_b32 s10, s31, 8
	v_ashrrev_i32_e32 v141, 31, v140
	v_readlane_b32 s12, v253, 0
	s_ashr_i32 s11, s10, 31
	v_lshlrev_b64 v[142:143], 11, v[140:141]
	v_readlane_b32 s13, v253, 1
	s_lshl_b64 s[10:11], s[10:11], 1
	v_cvt_pk_bf16_f32 v104, v104, v105
	v_lshl_add_u64 v[142:143], s[12:13], 0, v[142:143]
	v_lshl_add_u64 v[142:143], v[142:143], 0, s[10:11]
	v_lshl_add_u64 v[142:143], v[142:143], 0, s[0:1]
	v_lshl_add_u64 v[142:143], v[142:143], 0, v[188:189]
	v_cvt_pk_bf16_f32 v105, v106, v107
	v_and_b32_e32 v230, 16, v204
	v_lshrrev_b32_e32 v231, 1, v230
	v_add_u32_e32 v230, v230, v231
	v_mov_b32_e32 v231, v189
	v_mov_b64_e32 v[234:235], v[104:105]
	v_or_b32_e32 v104, 16, v140
	v_ashrrev_i32_e32 v105, 31, v104
	v_lshlrev_b64 v[104:105], 11, v[104:105]
	v_lshl_add_u64 v[104:105], s[12:13], 0, v[104:105]
	v_lshl_add_u64 v[104:105], v[104:105], 0, s[10:11]
	v_lshl_add_u64 v[104:105], v[104:105], 0, s[0:1]
	v_lshl_add_u64 v[104:105], v[104:105], 0, v[188:189]
	v_cvt_pk_bf16_f32 v88, v88, v89
	v_cvt_pk_bf16_f32 v89, v90, v91
	v_mov_b64_e32 v[238:239], v[88:89]
	v_or_b32_e32 v88, 32, v140
	v_ashrrev_i32_e32 v89, 31, v88
	v_lshlrev_b64 v[88:89], 11, v[88:89]
	v_lshl_add_u64 v[88:89], s[12:13], 0, v[88:89]
	v_lshl_add_u64 v[88:89], v[88:89], 0, s[10:11]
	v_lshl_add_u64 v[88:89], v[88:89], 0, s[0:1]
	v_lshl_add_u64 v[88:89], v[88:89], 0, v[188:189]
	v_cvt_pk_bf16_f32 v72, v72, v73
	v_cvt_pk_bf16_f32 v73, v74, v75
	v_mov_b64_e32 v[242:243], v[72:73]
	v_or_b32_e32 v72, 48, v140
	v_ashrrev_i32_e32 v73, 31, v72
	v_lshlrev_b64 v[72:73], 11, v[72:73]
	v_lshl_add_u64 v[72:73], s[12:13], 0, v[72:73]
	v_lshl_add_u64 v[72:73], v[72:73], 0, s[10:11]
	v_lshl_add_u64 v[72:73], v[72:73], 0, s[0:1]
	v_lshl_add_u64 v[72:73], v[72:73], 0, v[188:189]
	v_cvt_pk_bf16_f32 v64, v64, v65
	v_cvt_pk_bf16_f32 v65, v66, v67
	v_mov_b64_e32 v[246:247], v[64:65]
	v_add_u32_e32 v64, 0x80, v140
	v_ashrrev_i32_e32 v65, 31, v64
	v_lshlrev_b64 v[64:65], 11, v[64:65]
	v_lshl_add_u64 v[64:65], s[12:13], 0, v[64:65]
	v_lshl_add_u64 v[64:65], v[64:65], 0, s[10:11]
	v_lshl_add_u64 v[64:65], v[64:65], 0, s[0:1]
	v_lshl_add_u64 v[64:65], v[64:65], 0, v[188:189]
	v_cvt_pk_bf16_f32 v40, v40, v41
	v_cvt_pk_bf16_f32 v41, v42, v43
	global_store_dwordx2 v[64:65], v[40:41], off offset:288
	v_add_u32_e32 v40, 0x90, v140
	v_ashrrev_i32_e32 v41, 31, v40
	v_lshlrev_b64 v[40:41], 11, v[40:41]
	v_lshl_add_u64 v[40:41], s[12:13], 0, v[40:41]
	v_lshl_add_u64 v[40:41], v[40:41], 0, s[10:11]
	v_lshl_add_u64 v[40:41], v[40:41], 0, s[0:1]
	v_lshl_add_u64 v[40:41], v[40:41], 0, v[188:189]
	v_cvt_pk_bf16_f32 v24, v24, v25
	v_cvt_pk_bf16_f32 v25, v26, v27
	global_store_dwordx2 v[40:41], v[24:25], off offset:288
	v_add_u32_e32 v24, 0xa0, v140
	v_ashrrev_i32_e32 v25, 31, v24
	v_lshlrev_b64 v[24:25], 11, v[24:25]
	v_lshl_add_u64 v[24:25], s[12:13], 0, v[24:25]
	v_lshl_add_u64 v[24:25], v[24:25], 0, s[10:11]
	v_lshl_add_u64 v[24:25], v[24:25], 0, s[0:1]
	v_lshl_add_u64 v[24:25], v[24:25], 0, v[188:189]
	v_cvt_pk_bf16_f32 v8, v8, v9
	v_cvt_pk_bf16_f32 v9, v10, v11
	global_store_dwordx2 v[24:25], v[8:9], off offset:288
	v_add_u32_e32 v8, 0xb0, v140
	v_ashrrev_i32_e32 v9, 31, v8
	v_lshlrev_b64 v[8:9], 11, v[8:9]
	v_lshl_add_u64 v[8:9], s[12:13], 0, v[8:9]
	v_lshl_add_u64 v[8:9], v[8:9], 0, s[10:11]
	v_lshl_add_u64 v[8:9], v[8:9], 0, s[0:1]
	v_cvt_pk_bf16_f32 v106, v116, v117
	v_cvt_pk_bf16_f32 v107, v118, v119
	v_cvt_pk_bf16_f32 v90, v100, v101
	v_cvt_pk_bf16_f32 v91, v102, v103
	v_cvt_pk_bf16_f32 v74, v84, v85
	v_cvt_pk_bf16_f32 v75, v86, v87
	v_cvt_pk_bf16_f32 v42, v52, v53
	v_cvt_pk_bf16_f32 v43, v54, v55
	v_cvt_pk_bf16_f32 v26, v36, v37
	v_cvt_pk_bf16_f32 v27, v38, v39
	v_lshl_add_u64 v[8:9], v[8:9], 0, v[188:189]
	v_cvt_pk_bf16_f32 v10, v20, v21
	v_cvt_pk_bf16_f32 v11, v22, v23
	v_cvt_pk_bf16_f32 v124, v124, v125
	v_cvt_pk_bf16_f32 v125, v126, v127
	v_cvt_pk_bf16_f32 v120, v120, v121
	v_cvt_pk_bf16_f32 v121, v122, v123
	v_cvt_pk_bf16_f32 v112, v112, v113
	v_cvt_pk_bf16_f32 v113, v114, v115
	global_store_dwordx2 v[104:105], v[106:107], off
	v_cvt_pk_bf16_f32 v106, v108, v109
	v_cvt_pk_bf16_f32 v107, v110, v111
	v_cvt_pk_bf16_f32 v96, v96, v97
	v_cvt_pk_bf16_f32 v97, v98, v99
	global_store_dwordx2 v[88:89], v[90:91], off
	v_cvt_pk_bf16_f32 v90, v92, v93
	v_cvt_pk_bf16_f32 v91, v94, v95
	v_cvt_pk_bf16_f32 v80, v80, v81
	v_cvt_pk_bf16_f32 v81, v82, v83
	global_store_dwordx2 v[72:73], v[74:75], off
	v_cvt_pk_bf16_f32 v74, v76, v77
	v_cvt_pk_bf16_f32 v75, v78, v79
	v_cvt_pk_bf16_f32 v68, v68, v69
	v_cvt_pk_bf16_f32 v69, v70, v71
	v_cvt_pk_bf16_f32 v60, v60, v61
	v_cvt_pk_bf16_f32 v61, v62, v63
	v_cvt_pk_bf16_f32 v56, v56, v57
	v_cvt_pk_bf16_f32 v57, v58, v59
	v_cvt_pk_bf16_f32 v48, v48, v49
	v_cvt_pk_bf16_f32 v49, v50, v51
	global_store_dwordx2 v[40:41], v[42:43], off
	v_cvt_pk_bf16_f32 v42, v44, v45
	v_cvt_pk_bf16_f32 v43, v46, v47
	v_cvt_pk_bf16_f32 v32, v32, v33
	v_cvt_pk_bf16_f32 v33, v34, v35
	global_store_dwordx2 v[24:25], v[26:27], off
	v_cvt_pk_bf16_f32 v26, v28, v29
	v_cvt_pk_bf16_f32 v27, v30, v31
	v_cvt_pk_bf16_f32 v16, v16, v17
	v_cvt_pk_bf16_f32 v17, v18, v19
	global_store_dwordx2 v[8:9], v[10:11], off
	v_cvt_pk_bf16_f32 v10, v12, v13
	v_cvt_pk_bf16_f32 v11, v14, v15
	v_cvt_pk_bf16_f32 v4, v4, v5
	v_cvt_pk_bf16_f32 v5, v6, v7
	v_cvt_pk_bf16_f32 v0, v0, v1
	v_cvt_pk_bf16_f32 v1, v2, v3
	s_and_b64 vcc, exec, s[2:3]
	s_mov_b32 s31, s29
	s_mov_b32 s33, s30
	s_mov_b64 s[12:13], s[4:5]
	s_mov_b64 s[10:11], s[8:9]
	global_store_dwordx2 v[142:143], v[124:125], off
	global_store_dwordx2 v[142:143], v[120:121], off offset:32
	v_mov_b64_e32 v[232:233], v[112:113]
	s_nop 1
	v_permlane16_swap_b32 v232, v234
	v_permlane16_swap_b32 v233, v235
	v_lshl_add_u64 v[248:249], v[142:143], 0, v[230:231]
	global_store_dwordx4 v[248:249], v[232:235], off offset:256
	s_nop 1
	global_store_dwordx2 v[104:105], v[106:107], off offset:32
	v_mov_b64_e32 v[236:237], v[96:97]
	s_nop 1
	v_permlane16_swap_b32 v236, v238
	v_permlane16_swap_b32 v237, v239
	v_lshl_add_u64 v[248:249], v[104:105], 0, v[230:231]
	global_store_dwordx4 v[248:249], v[236:239], off offset:256
	s_nop 1
	global_store_dwordx2 v[88:89], v[90:91], off offset:32
	v_mov_b64_e32 v[240:241], v[80:81]
	s_nop 1
	v_permlane16_swap_b32 v240, v242
	v_permlane16_swap_b32 v241, v243
	v_lshl_add_u64 v[248:249], v[88:89], 0, v[230:231]
	global_store_dwordx4 v[248:249], v[240:243], off offset:256
	s_nop 1
	global_store_dwordx2 v[72:73], v[74:75], off offset:32
	v_mov_b64_e32 v[244:245], v[68:69]
	s_nop 1
	v_permlane16_swap_b32 v244, v246
	v_permlane16_swap_b32 v245, v247
	v_lshl_add_u64 v[248:249], v[72:73], 0, v[230:231]
	global_store_dwordx4 v[248:249], v[244:247], off offset:256
	s_nop 1
	v_mov_b64_e32 v[232:233], v[60:61]
	v_mov_b64_e32 v[234:235], v[56:57]
	s_nop 1
	v_permlane16_swap_b32 v232, v234
	v_permlane16_swap_b32 v233, v235
	v_lshl_add_u64 v[248:249], v[64:65], 0, v[230:231]
	global_store_dwordx4 v[248:249], v[232:235], off
	s_nop 1
	global_store_dwordx2 v[64:65], v[48:49], off offset:256
	global_store_dwordx2 v[40:41], v[42:43], off offset:32
	global_store_dwordx2 v[40:41], v[32:33], off offset:256
	global_store_dwordx2 v[24:25], v[26:27], off offset:32
	global_store_dwordx2 v[24:25], v[16:17], off offset:256
	global_store_dwordx2 v[8:9], v[10:11], off offset:32
	v_mov_b64_e32 v[232:233], v[4:5]
	v_mov_b64_e32 v[234:235], v[0:1]
	s_nop 1
	v_permlane16_swap_b32 v232, v234
	v_permlane16_swap_b32 v233, v235
	v_lshl_add_u64 v[248:249], v[8:9], 0, v[230:231]
	global_store_dwordx4 v[248:249], v[232:235], off offset:256
	s_nop 1
	s_cbranch_vccz .LBB0_103
	s_waitcnt vmcnt(0)
	s_cmpk_gt_u32 s18, 0xff
	s_mov_b32 s28, 0x8000
	s_movk_i32 s29, 0xc0
	s_mov_b32 s30, 0x800000
	s_movk_i32 s31, 0x7fff
	s_movk_i32 s33, 0x1800
	s_cbranch_scc1 .LBB0_114
	s_barrier

.LBB0_150:
	s_add_u32 s16, s14, 0xfffc0080
	s_addc_u32 s17, s15, -1
	s_add_i32 s39, 0, 0x10000
	v_add_u32_e32 v139, s39, v137
	ds_read_b128 v[140:143], v139
	ds_read_b128 v[144:147], v139 offset:1024
	ds_read_b128 v[148:151], v139 offset:2048
	ds_read_b128 v[152:155], v139 offset:3072
	s_cmp_eq_u32 s38, 12
	s_cselect_b32 s19, s3, s17
	s_cselect_b32 s18, s34, s16
	s_cselect_b32 s17, s5, s37
	s_cselect_b32 s16, s35, s36
	v_lshl_add_u64 v[190:191], s[14:15], 0, v[132:133]
	s_add_i32 m0, s24, 0xc000
	ds_read_b128 v[156:159], v138
	ds_read_b128 v[160:163], v138 offset:1024
	ds_read_b128 v[164:167], v138 offset:2048
	ds_read_b128 v[168:171], v138 offset:3072
	ds_read_b128 v[172:175], v138 offset:4096
	ds_read_b128 v[176:179], v138 offset:5120
	ds_read_b128 v[180:183], v138 offset:6144
	ds_read_b128 v[184:187], v138 offset:7168
	global_load_lds_dwordx4 v[190:191], off
	v_lshl_add_u64 v[190:191], s[14:15], 0, v[134:135]
	s_add_i32 m0, s24, 0xe000
	s_nop 0
	global_load_lds_dwordx4 v[190:191], off
	s_waitcnt lgkmcnt(8)
	s_barrier
	s_waitcnt lgkmcnt(0)
	s_setprio 1
	s_waitcnt lgkmcnt(0)
	v_mfma_f32_16x16x32_bf16 v[124:127], v[140:143], v[156:159], v[124:127]
	v_mfma_f32_16x16x32_bf16 v[120:123], v[148:151], v[156:159], v[120:123]
	v_mfma_f32_16x16x32_bf16 v[116:119], v[140:143], v[164:167], v[116:119]
	v_mfma_f32_16x16x32_bf16 v[108:111], v[148:151], v[164:167], v[108:111]
	v_mfma_f32_16x16x32_bf16 v[100:103], v[140:143], v[172:175], v[100:103]
	v_mfma_f32_16x16x32_bf16 v[92:95], v[148:151], v[172:175], v[92:95]
	v_mfma_f32_16x16x32_bf16 v[84:87], v[140:143], v[180:183], v[84:87]
	v_mfma_f32_16x16x32_bf16 v[76:79], v[148:151], v[180:183], v[76:79]
	v_mfma_f32_16x16x32_bf16 v[124:127], v[144:147], v[160:163], v[124:127]
	v_mfma_f32_16x16x32_bf16 v[120:123], v[152:155], v[160:163], v[120:123]
	v_mfma_f32_16x16x32_bf16 v[116:119], v[144:147], v[168:171], v[116:119]
	v_mfma_f32_16x16x32_bf16 v[108:111], v[152:155], v[168:171], v[108:111]
	v_mfma_f32_16x16x32_bf16 v[100:103], v[144:147], v[176:179], v[100:103]
	v_mfma_f32_16x16x32_bf16 v[92:95], v[152:155], v[176:179], v[92:95]
	v_mfma_f32_16x16x32_bf16 v[84:87], v[144:147], v[184:187], v[84:87]
	v_mfma_f32_16x16x32_bf16 v[76:79], v[152:155], v[184:187], v[76:79]
	s_setprio 0
	s_barrier
	s_add_i32 s42, 0, 0x14000
	s_add_i32 s39, s39, s23
	v_add_u32_e32 v139, s42, v137
	v_lshl_add_u64 v[202:203], s[16:17], 0, v[130:131]
	s_mov_b32 m0, s39
	ds_read_b128 v[190:193], v139
	ds_read_b128 v[194:197], v139 offset:1024
	ds_read_b128 v[198:201], v139 offset:2048
	ds_read_b128 v[216:219], v139 offset:3072
	global_load_lds_dwordx4 v[202:203], off
	v_lshl_add_u64 v[220:221], s[16:17], 0, v[128:129]
	s_add_i32 m0, s39, 0x2000
	s_nop 0
	global_load_lds_dwordx4 v[220:221], off
	s_barrier
	s_waitcnt lgkmcnt(0)
	s_setprio 1
	s_waitcnt lgkmcnt(0)
	v_mfma_f32_16x16x32_bf16 v[112:115], v[190:193], v[156:159], v[112:115]
	v_mfma_f32_16x16x32_bf16 v[104:107], v[198:201], v[156:159], v[104:107]
	v_mfma_f32_16x16x32_bf16 v[96:99], v[190:193], v[164:167], v[96:99]
	v_mfma_f32_16x16x32_bf16 v[88:91], v[198:201], v[164:167], v[88:91]
	v_mfma_f32_16x16x32_bf16 v[80:83], v[190:193], v[172:175], v[80:83]
	v_mfma_f32_16x16x32_bf16 v[72:75], v[198:201], v[172:175], v[72:75]
	v_mfma_f32_16x16x32_bf16 v[68:71], v[190:193], v[180:183], v[68:71]
	v_mfma_f32_16x16x32_bf16 v[64:67], v[198:201], v[180:183], v[64:67]
	v_mfma_f32_16x16x32_bf16 v[112:115], v[194:197], v[160:163], v[112:115]
	v_mfma_f32_16x16x32_bf16 v[104:107], v[216:219], v[160:163], v[104:107]
	v_mfma_f32_16x16x32_bf16 v[96:99], v[194:197], v[168:171], v[96:99]
	v_mfma_f32_16x16x32_bf16 v[88:91], v[216:219], v[168:171], v[88:91]
	v_mfma_f32_16x16x32_bf16 v[80:83], v[194:197], v[176:179], v[80:83]
	v_mfma_f32_16x16x32_bf16 v[72:75], v[216:219], v[176:179], v[72:75]
	v_mfma_f32_16x16x32_bf16 v[68:71], v[194:197], v[184:187], v[68:71]
	v_mfma_f32_16x16x32_bf16 v[64:67], v[216:219], v[184:187], v[64:67]
	s_setprio 0
	s_mov_b32 m0, s24
	v_lshl_add_u64 v[222:223], s[18:19], 0, v[130:131]
	s_barrier
	ds_read_b128 v[156:159], v138 offset:16384
	ds_read_b128 v[160:163], v138 offset:17408
	ds_read_b128 v[164:167], v138 offset:18432
	ds_read_b128 v[168:171], v138 offset:19456
	ds_read_b128 v[172:175], v138 offset:20480
	ds_read_b128 v[176:179], v138 offset:21504
	ds_read_b128 v[180:183], v138 offset:22528
	ds_read_b128 v[184:187], v138 offset:23552
	global_load_lds_dwordx4 v[222:223], off
	v_lshl_add_u64 v[224:225], s[18:19], 0, v[128:129]
	s_mov_b32 m0, s25
	s_nop 0
	global_load_lds_dwordx4 v[224:225], off
	s_barrier
	s_waitcnt lgkmcnt(0)
	s_setprio 1
	s_waitcnt lgkmcnt(0)
	v_mfma_f32_16x16x32_bf16 v[60:63], v[140:143], v[156:159], v[60:63]
	v_mfma_f32_16x16x32_bf16 v[56:59], v[148:151], v[156:159], v[56:59]
	v_mfma_f32_16x16x32_bf16 v[52:55], v[140:143], v[164:167], v[52:55]
	v_mfma_f32_16x16x32_bf16 v[44:47], v[148:151], v[164:167], v[44:47]
	v_mfma_f32_16x16x32_bf16 v[36:39], v[140:143], v[172:175], v[36:39]
	v_mfma_f32_16x16x32_bf16 v[28:31], v[148:151], v[172:175], v[28:31]
	v_mfma_f32_16x16x32_bf16 v[20:23], v[140:143], v[180:183], v[20:23]
	v_mfma_f32_16x16x32_bf16 v[12:15], v[148:151], v[180:183], v[12:15]
	v_mfma_f32_16x16x32_bf16 v[60:63], v[144:147], v[160:163], v[60:63]
	v_mfma_f32_16x16x32_bf16 v[56:59], v[152:155], v[160:163], v[56:59]
	v_mfma_f32_16x16x32_bf16 v[52:55], v[144:147], v[168:171], v[52:55]
	v_mfma_f32_16x16x32_bf16 v[44:47], v[152:155], v[168:171], v[44:47]
	v_mfma_f32_16x16x32_bf16 v[36:39], v[144:147], v[176:179], v[36:39]
	v_mfma_f32_16x16x32_bf16 v[28:31], v[152:155], v[176:179], v[28:31]
	v_mfma_f32_16x16x32_bf16 v[20:23], v[144:147], v[184:187], v[20:23]
	v_mfma_f32_16x16x32_bf16 v[12:15], v[152:155], v[184:187], v[12:15]
	s_setprio 0
	s_barrier
	s_add_u32 s40, s16, 0x40000
	s_addc_u32 s41, s17, 0
	s_add_i32 s39, s42, s23
	v_lshl_add_u64 v[140:141], s[40:41], 0, v[130:131]
	s_mov_b32 m0, s39
	s_nop 0
	global_load_lds_dwordx4 v[140:141], off
	v_lshl_add_u64 v[140:141], s[40:41], 0, v[128:129]
	s_add_i32 m0, s39, 0x2000
	s_nop 0
	global_load_lds_dwordx4 v[140:141], off
	s_waitcnt vmcnt(6)
	s_barrier
	s_setprio 1
	v_mfma_f32_16x16x32_bf16 v[48:51], v[190:193], v[156:159], v[48:51]
	v_mfma_f32_16x16x32_bf16 v[40:43], v[198:201], v[156:159], v[40:43]
	v_mfma_f32_16x16x32_bf16 v[32:35], v[190:193], v[164:167], v[32:35]
	v_mfma_f32_16x16x32_bf16 v[24:27], v[198:201], v[164:167], v[24:27]
	v_mfma_f32_16x16x32_bf16 v[16:19], v[190:193], v[172:175], v[16:19]
	v_mfma_f32_16x16x32_bf16 v[8:11], v[198:201], v[172:175], v[8:11]
	v_mfma_f32_16x16x32_bf16 v[4:7], v[190:193], v[180:183], v[4:7]
	v_mfma_f32_16x16x32_bf16 v[0:3], v[198:201], v[180:183], v[0:3]
	v_mfma_f32_16x16x32_bf16 v[48:51], v[194:197], v[160:163], v[48:51]
	v_mfma_f32_16x16x32_bf16 v[40:43], v[216:219], v[160:163], v[40:43]
	v_mfma_f32_16x16x32_bf16 v[32:35], v[194:197], v[168:171], v[32:35]
	v_mfma_f32_16x16x32_bf16 v[24:27], v[216:219], v[168:171], v[24:27]
	v_mfma_f32_16x16x32_bf16 v[16:19], v[194:197], v[176:179], v[16:19]
	v_mfma_f32_16x16x32_bf16 v[8:11], v[216:219], v[176:179], v[8:11]
	v_mfma_f32_16x16x32_bf16 v[4:7], v[194:197], v[184:187], v[4:7]
	v_mfma_f32_16x16x32_bf16 v[0:3], v[216:219], v[184:187], v[0:3]
	s_setprio 0
	s_add_i32 s39, 0, 0x18000
	v_add_u32_e32 v139, s39, v137
	s_barrier
	ds_read_b128 v[140:143], v139
	ds_read_b128 v[144:147], v139 offset:1024
	ds_read_b128 v[148:151], v139 offset:2048
	ds_read_b128 v[152:155], v139 offset:3072
	s_add_u32 s18, s18, 0x40000
	s_addc_u32 s19, s19, 0
	s_mov_b32 m0, s26
	v_lshl_add_u64 v[190:191], s[18:19], 0, v[130:131]
	ds_read_b128 v[156:159], v138 offset:32768
	ds_read_b128 v[160:163], v138 offset:33792
	ds_read_b128 v[164:167], v138 offset:34816
	ds_read_b128 v[168:171], v138 offset:35840
	ds_read_b128 v[172:175], v138 offset:36864
	ds_read_b128 v[176:179], v138 offset:37888
	ds_read_b128 v[180:183], v138 offset:38912
	ds_read_b128 v[184:187], v138 offset:39936
	global_load_lds_dwordx4 v[190:191], off
	v_lshl_add_u64 v[190:191], s[18:19], 0, v[128:129]
	s_mov_b32 m0, s27
	s_nop 0
	global_load_lds_dwordx4 v[190:191], off
	s_waitcnt lgkmcnt(8)
	s_barrier
	s_waitcnt lgkmcnt(0)
	s_setprio 1
	s_waitcnt lgkmcnt(0)
	v_mfma_f32_16x16x32_bf16 v[124:127], v[140:143], v[156:159], v[124:127]
	v_mfma_f32_16x16x32_bf16 v[120:123], v[148:151], v[156:159], v[120:123]
	v_mfma_f32_16x16x32_bf16 v[116:119], v[140:143], v[164:167], v[116:119]
	v_mfma_f32_16x16x32_bf16 v[108:111], v[148:151], v[164:167], v[108:111]
	v_mfma_f32_16x16x32_bf16 v[100:103], v[140:143], v[172:175], v[100:103]
	v_mfma_f32_16x16x32_bf16 v[92:95], v[148:151], v[172:175], v[92:95]
	v_mfma_f32_16x16x32_bf16 v[84:87], v[140:143], v[180:183], v[84:87]
	v_mfma_f32_16x16x32_bf16 v[76:79], v[148:151], v[180:183], v[76:79]
	v_mfma_f32_16x16x32_bf16 v[124:127], v[144:147], v[160:163], v[124:127]
	v_mfma_f32_16x16x32_bf16 v[120:123], v[152:155], v[160:163], v[120:123]
	v_mfma_f32_16x16x32_bf16 v[116:119], v[144:147], v[168:171], v[116:119]
	v_mfma_f32_16x16x32_bf16 v[108:111], v[152:155], v[168:171], v[108:111]
	v_mfma_f32_16x16x32_bf16 v[100:103], v[144:147], v[176:179], v[100:103]
	v_mfma_f32_16x16x32_bf16 v[92:95], v[152:155], v[176:179], v[92:95]
	v_mfma_f32_16x16x32_bf16 v[84:87], v[144:147], v[184:187], v[84:87]
	v_mfma_f32_16x16x32_bf16 v[76:79], v[152:155], v[184:187], v[76:79]
	s_setprio 0
	s_barrier
	s_add_i32 s18, 0, 0x1c000
	s_add_i32 s19, s39, s23
	v_add_u32_e32 v139, s18, v137
	v_lshl_add_u64 v[202:203], v[202:203], 0, s[92:93]
	s_mov_b32 m0, s19
	ds_read_b128 v[190:193], v139
	ds_read_b128 v[194:197], v139 offset:1024
	ds_read_b128 v[198:201], v139 offset:2048
	ds_read_b128 v[216:219], v139 offset:3072
	global_load_lds_dwordx4 v[202:203], off
	v_lshl_add_u64 v[202:203], v[220:221], 0, s[92:93]
	s_add_i32 m0, s19, 0x2000
	s_nop 0
	global_load_lds_dwordx4 v[202:203], off
	s_barrier
	s_waitcnt lgkmcnt(0)
	s_setprio 1
	s_waitcnt lgkmcnt(0)
	v_mfma_f32_16x16x32_bf16 v[112:115], v[190:193], v[156:159], v[112:115]
	v_mfma_f32_16x16x32_bf16 v[104:107], v[198:201], v[156:159], v[104:107]
	v_mfma_f32_16x16x32_bf16 v[96:99], v[190:193], v[164:167], v[96:99]
	v_mfma_f32_16x16x32_bf16 v[88:91], v[198:201], v[164:167], v[88:91]
	v_mfma_f32_16x16x32_bf16 v[80:83], v[190:193], v[172:175], v[80:83]
	v_mfma_f32_16x16x32_bf16 v[72:75], v[198:201], v[172:175], v[72:75]
	v_mfma_f32_16x16x32_bf16 v[68:71], v[190:193], v[180:183], v[68:71]
	v_mfma_f32_16x16x32_bf16 v[64:67], v[198:201], v[180:183], v[64:67]
	v_mfma_f32_16x16x32_bf16 v[112:115], v[194:197], v[160:163], v[112:115]
	v_mfma_f32_16x16x32_bf16 v[104:107], v[216:219], v[160:163], v[104:107]
	v_mfma_f32_16x16x32_bf16 v[96:99], v[194:197], v[168:171], v[96:99]
	v_mfma_f32_16x16x32_bf16 v[88:91], v[216:219], v[168:171], v[88:91]
	v_mfma_f32_16x16x32_bf16 v[80:83], v[194:197], v[176:179], v[80:83]
	v_mfma_f32_16x16x32_bf16 v[72:75], v[216:219], v[176:179], v[72:75]
	v_mfma_f32_16x16x32_bf16 v[68:71], v[194:197], v[184:187], v[68:71]
	v_mfma_f32_16x16x32_bf16 v[64:67], v[216:219], v[184:187], v[64:67]
	s_setprio 0
	s_mov_b32 m0, s28
	v_lshl_add_u64 v[202:203], v[222:223], 0, s[92:93]
	s_barrier
	ds_read_b128 v[156:159], v138 offset:49152
	ds_read_b128 v[160:163], v138 offset:50176
	ds_read_b128 v[164:167], v138 offset:51200
	ds_read_b128 v[168:171], v138 offset:52224
	ds_read_b128 v[172:175], v138 offset:53248
	ds_read_b128 v[176:179], v138 offset:54272
	ds_read_b128 v[180:183], v138 offset:55296
	ds_read_b128 v[184:187], v138 offset:56320
	global_load_lds_dwordx4 v[202:203], off
	v_lshl_add_u64 v[202:203], v[224:225], 0, s[92:93]
	s_mov_b32 m0, s29
	s_nop 0
	global_load_lds_dwordx4 v[202:203], off
	s_barrier
	s_waitcnt lgkmcnt(0)
	s_setprio 1
	s_waitcnt lgkmcnt(0)
	v_mfma_f32_16x16x32_bf16 v[60:63], v[140:143], v[156:159], v[60:63]
	v_mfma_f32_16x16x32_bf16 v[56:59], v[148:151], v[156:159], v[56:59]
	v_mfma_f32_16x16x32_bf16 v[52:55], v[140:143], v[164:167], v[52:55]
	v_mfma_f32_16x16x32_bf16 v[44:47], v[148:151], v[164:167], v[44:47]
	v_mfma_f32_16x16x32_bf16 v[36:39], v[140:143], v[172:175], v[36:39]
	v_mfma_f32_16x16x32_bf16 v[28:31], v[148:151], v[172:175], v[28:31]
	v_mfma_f32_16x16x32_bf16 v[20:23], v[140:143], v[180:183], v[20:23]
	v_mfma_f32_16x16x32_bf16 v[12:15], v[148:151], v[180:183], v[12:15]
	v_mfma_f32_16x16x32_bf16 v[60:63], v[144:147], v[160:163], v[60:63]
	v_mfma_f32_16x16x32_bf16 v[56:59], v[152:155], v[160:163], v[56:59]
	v_mfma_f32_16x16x32_bf16 v[52:55], v[144:147], v[168:171], v[52:55]
	v_mfma_f32_16x16x32_bf16 v[44:47], v[152:155], v[168:171], v[44:47]
	v_mfma_f32_16x16x32_bf16 v[36:39], v[144:147], v[176:179], v[36:39]
	v_mfma_f32_16x16x32_bf16 v[28:31], v[152:155], v[176:179], v[28:31]
	v_mfma_f32_16x16x32_bf16 v[20:23], v[144:147], v[184:187], v[20:23]
	v_mfma_f32_16x16x32_bf16 v[12:15], v[152:155], v[184:187], v[12:15]
	s_setprio 0
	s_barrier
	s_add_u32 s16, s16, 0x40080
	s_addc_u32 s17, s17, 0
	s_add_i32 s18, s18, s23
	v_lshl_add_u64 v[140:141], s[16:17], 0, v[130:131]
	s_mov_b32 m0, s18
	s_nop 0
	global_load_lds_dwordx4 v[140:141], off
	v_lshl_add_u64 v[140:141], s[16:17], 0, v[128:129]
	s_add_i32 m0, s18, 0x2000
	s_nop 0
	global_load_lds_dwordx4 v[140:141], off
	s_waitcnt vmcnt(6)
	s_barrier
	s_setprio 1
	v_mfma_f32_16x16x32_bf16 v[48:51], v[190:193], v[156:159], v[48:51]
	v_mfma_f32_16x16x32_bf16 v[40:43], v[198:201], v[156:159], v[40:43]
	v_mfma_f32_16x16x32_bf16 v[32:35], v[190:193], v[164:167], v[32:35]
	v_mfma_f32_16x16x32_bf16 v[24:27], v[198:201], v[164:167], v[24:27]
	v_mfma_f32_16x16x32_bf16 v[16:19], v[190:193], v[172:175], v[16:19]
	v_mfma_f32_16x16x32_bf16 v[8:11], v[198:201], v[172:175], v[8:11]
	v_mfma_f32_16x16x32_bf16 v[4:7], v[190:193], v[180:183], v[4:7]
	v_mfma_f32_16x16x32_bf16 v[0:3], v[198:201], v[180:183], v[0:3]
	v_mfma_f32_16x16x32_bf16 v[48:51], v[194:197], v[160:163], v[48:51]
	v_mfma_f32_16x16x32_bf16 v[40:43], v[216:219], v[160:163], v[40:43]
	v_mfma_f32_16x16x32_bf16 v[32:35], v[194:197], v[168:171], v[32:35]
	v_mfma_f32_16x16x32_bf16 v[24:27], v[216:219], v[168:171], v[24:27]
	v_mfma_f32_16x16x32_bf16 v[16:19], v[194:197], v[176:179], v[16:19]
	v_mfma_f32_16x16x32_bf16 v[8:11], v[216:219], v[176:179], v[8:11]
	v_mfma_f32_16x16x32_bf16 v[4:7], v[194:197], v[184:187], v[4:7]
	v_mfma_f32_16x16x32_bf16 v[0:3], v[216:219], v[184:187], v[0:3]
	s_setprio 0
	s_add_i32 s38, s38, 2
	s_add_u32 s14, s14, 0x100
	s_addc_u32 s15, s15, 0
	s_add_u32 s36, s36, 0x100
	s_addc_u32 s37, s37, 0
	s_cmp_gt_u32 s38, 13
	s_barrier
	s_cbranch_scc0 .LBB0_150
	v_lshl_add_u32 v140, s33, 8, v136
	s_lshl_b32 s14, s31, 8
	v_ashrrev_i32_e32 v141, 31, v140
	v_readlane_b32 s16, v252, 62
	s_ashr_i32 s15, s14, 31
	v_lshlrev_b64 v[142:143], 11, v[140:141]
	v_readlane_b32 s17, v252, 63
	s_lshl_b64 s[14:15], s[14:15], 1
	v_cvt_pk_bf16_f32 v104, v104, v105
	v_lshl_add_u64 v[142:143], s[16:17], 0, v[142:143]
	v_lshl_add_u64 v[142:143], v[142:143], 0, s[14:15]
	v_lshl_add_u64 v[142:143], v[142:143], 0, s[0:1]
	v_lshl_add_u64 v[142:143], v[142:143], 0, v[188:189]
	v_cvt_pk_bf16_f32 v105, v106, v107
	v_and_b32_e32 v230, 16, v204
	v_lshrrev_b32_e32 v231, 1, v230
	v_add_u32_e32 v230, v230, v231
	v_mov_b32_e32 v231, v189
	v_mov_b64_e32 v[234:235], v[104:105]
	v_or_b32_e32 v104, 16, v140
	v_ashrrev_i32_e32 v105, 31, v104
	v_lshlrev_b64 v[104:105], 11, v[104:105]
	v_lshl_add_u64 v[104:105], s[16:17], 0, v[104:105]
	v_lshl_add_u64 v[104:105], v[104:105], 0, s[14:15]
	v_lshl_add_u64 v[104:105], v[104:105], 0, s[0:1]
	v_lshl_add_u64 v[104:105], v[104:105], 0, v[188:189]
	v_cvt_pk_bf16_f32 v88, v88, v89
	v_cvt_pk_bf16_f32 v89, v90, v91
	v_mov_b64_e32 v[238:239], v[88:89]
	v_or_b32_e32 v88, 32, v140
	v_ashrrev_i32_e32 v89, 31, v88
	v_lshlrev_b64 v[88:89], 11, v[88:89]
	v_lshl_add_u64 v[88:89], s[16:17], 0, v[88:89]
	v_lshl_add_u64 v[88:89], v[88:89], 0, s[14:15]
	v_lshl_add_u64 v[88:89], v[88:89], 0, s[0:1]
	v_lshl_add_u64 v[88:89], v[88:89], 0, v[188:189]
	v_cvt_pk_bf16_f32 v72, v72, v73
	v_cvt_pk_bf16_f32 v73, v74, v75
	v_mov_b64_e32 v[242:243], v[72:73]
	v_or_b32_e32 v72, 48, v140
	v_ashrrev_i32_e32 v73, 31, v72
	v_lshlrev_b64 v[72:73], 11, v[72:73]
	v_lshl_add_u64 v[72:73], s[16:17], 0, v[72:73]
	v_lshl_add_u64 v[72:73], v[72:73], 0, s[14:15]
	v_lshl_add_u64 v[72:73], v[72:73], 0, s[0:1]
	v_lshl_add_u64 v[72:73], v[72:73], 0, v[188:189]
	v_cvt_pk_bf16_f32 v64, v64, v65
	v_cvt_pk_bf16_f32 v65, v66, v67
	v_mov_b64_e32 v[246:247], v[64:65]
	v_add_u32_e32 v64, 0x80, v140
	v_ashrrev_i32_e32 v65, 31, v64
	v_lshlrev_b64 v[64:65], 11, v[64:65]
	v_lshl_add_u64 v[64:65], s[16:17], 0, v[64:65]
	v_lshl_add_u64 v[64:65], v[64:65], 0, s[14:15]
	v_lshl_add_u64 v[64:65], v[64:65], 0, s[0:1]
	v_lshl_add_u64 v[64:65], v[64:65], 0, v[188:189]
	v_cvt_pk_bf16_f32 v40, v40, v41
	v_cvt_pk_bf16_f32 v41, v42, v43
	global_store_dwordx2 v[64:65], v[40:41], off offset:288
	v_add_u32_e32 v40, 0x90, v140
	v_ashrrev_i32_e32 v41, 31, v40
	v_lshlrev_b64 v[40:41], 11, v[40:41]
	v_lshl_add_u64 v[40:41], s[16:17], 0, v[40:41]
	v_lshl_add_u64 v[40:41], v[40:41], 0, s[14:15]
	v_lshl_add_u64 v[40:41], v[40:41], 0, s[0:1]
	v_lshl_add_u64 v[40:41], v[40:41], 0, v[188:189]
	v_cvt_pk_bf16_f32 v24, v24, v25
	v_cvt_pk_bf16_f32 v25, v26, v27
	global_store_dwordx2 v[40:41], v[24:25], off offset:288
	v_add_u32_e32 v24, 0xa0, v140
	v_ashrrev_i32_e32 v25, 31, v24
	v_lshlrev_b64 v[24:25], 11, v[24:25]
	v_lshl_add_u64 v[24:25], s[16:17], 0, v[24:25]
	v_lshl_add_u64 v[24:25], v[24:25], 0, s[14:15]
	v_lshl_add_u64 v[24:25], v[24:25], 0, s[0:1]
	v_lshl_add_u64 v[24:25], v[24:25], 0, v[188:189]
	v_cvt_pk_bf16_f32 v8, v8, v9
	v_cvt_pk_bf16_f32 v9, v10, v11
	global_store_dwordx2 v[24:25], v[8:9], off offset:288
	v_add_u32_e32 v8, 0xb0, v140
	v_ashrrev_i32_e32 v9, 31, v8
	v_lshlrev_b64 v[8:9], 11, v[8:9]
	v_lshl_add_u64 v[8:9], s[16:17], 0, v[8:9]
	v_lshl_add_u64 v[8:9], v[8:9], 0, s[14:15]
	v_lshl_add_u64 v[8:9], v[8:9], 0, s[0:1]
	v_cvt_pk_bf16_f32 v106, v116, v117
	v_cvt_pk_bf16_f32 v107, v118, v119
	v_cvt_pk_bf16_f32 v90, v100, v101
	v_cvt_pk_bf16_f32 v91, v102, v103
	v_cvt_pk_bf16_f32 v74, v84, v85
	v_cvt_pk_bf16_f32 v75, v86, v87
	v_cvt_pk_bf16_f32 v42, v52, v53
	v_cvt_pk_bf16_f32 v43, v54, v55
	v_cvt_pk_bf16_f32 v26, v36, v37
	v_cvt_pk_bf16_f32 v27, v38, v39
	v_lshl_add_u64 v[8:9], v[8:9], 0, v[188:189]
	v_cvt_pk_bf16_f32 v10, v20, v21
	v_cvt_pk_bf16_f32 v11, v22, v23
	v_cvt_pk_bf16_f32 v124, v124, v125
	v_cvt_pk_bf16_f32 v125, v126, v127
	v_cvt_pk_bf16_f32 v120, v120, v121
	v_cvt_pk_bf16_f32 v121, v122, v123
	v_cvt_pk_bf16_f32 v112, v112, v113
	v_cvt_pk_bf16_f32 v113, v114, v115
	global_store_dwordx2 v[104:105], v[106:107], off
	v_cvt_pk_bf16_f32 v106, v108, v109
	v_cvt_pk_bf16_f32 v107, v110, v111
	v_cvt_pk_bf16_f32 v96, v96, v97
	v_cvt_pk_bf16_f32 v97, v98, v99
	global_store_dwordx2 v[88:89], v[90:91], off
	v_cvt_pk_bf16_f32 v90, v92, v93
	v_cvt_pk_bf16_f32 v91, v94, v95
	v_cvt_pk_bf16_f32 v80, v80, v81
	v_cvt_pk_bf16_f32 v81, v82, v83
	global_store_dwordx2 v[72:73], v[74:75], off
	v_cvt_pk_bf16_f32 v74, v76, v77
	v_cvt_pk_bf16_f32 v75, v78, v79
	v_cvt_pk_bf16_f32 v68, v68, v69
	v_cvt_pk_bf16_f32 v69, v70, v71
	v_cvt_pk_bf16_f32 v60, v60, v61
	v_cvt_pk_bf16_f32 v61, v62, v63
	v_cvt_pk_bf16_f32 v56, v56, v57
	v_cvt_pk_bf16_f32 v57, v58, v59
	v_cvt_pk_bf16_f32 v48, v48, v49
	v_cvt_pk_bf16_f32 v49, v50, v51
	global_store_dwordx2 v[40:41], v[42:43], off
	v_cvt_pk_bf16_f32 v42, v44, v45
	v_cvt_pk_bf16_f32 v43, v46, v47
	v_cvt_pk_bf16_f32 v32, v32, v33
	v_cvt_pk_bf16_f32 v33, v34, v35
	global_store_dwordx2 v[24:25], v[26:27], off
	v_cvt_pk_bf16_f32 v26, v28, v29
	v_cvt_pk_bf16_f32 v27, v30, v31
	v_cvt_pk_bf16_f32 v16, v16, v17
	v_cvt_pk_bf16_f32 v17, v18, v19
	global_store_dwordx2 v[8:9], v[10:11], off
	v_cvt_pk_bf16_f32 v10, v12, v13
	v_cvt_pk_bf16_f32 v11, v14, v15
	v_cvt_pk_bf16_f32 v4, v4, v5
	v_cvt_pk_bf16_f32 v5, v6, v7
	v_cvt_pk_bf16_f32 v0, v0, v1
	v_cvt_pk_bf16_f32 v1, v2, v3
	s_and_b64 vcc, exec, s[8:9]
	s_mov_b32 s31, s4
	s_mov_b32 s33, s2
	s_mov_b64 s[16:17], s[12:13]
	s_mov_b64 s[14:15], s[10:11]
	global_store_dwordx2 v[142:143], v[124:125], off
	global_store_dwordx2 v[142:143], v[120:121], off offset:32
	v_mov_b64_e32 v[232:233], v[112:113]
	s_nop 1
	v_permlane16_swap_b32 v232, v234
	v_permlane16_swap_b32 v233, v235
	v_lshl_add_u64 v[248:249], v[142:143], 0, v[230:231]
	global_store_dwordx4 v[248:249], v[232:235], off offset:256
	s_nop 1
	global_store_dwordx2 v[104:105], v[106:107], off offset:32
	v_mov_b64_e32 v[236:237], v[96:97]
	s_nop 1
	v_permlane16_swap_b32 v236, v238
	v_permlane16_swap_b32 v237, v239
	v_lshl_add_u64 v[248:249], v[104:105], 0, v[230:231]
	global_store_dwordx4 v[248:249], v[236:239], off offset:256
	s_nop 1
	global_store_dwordx2 v[88:89], v[90:91], off offset:32
	v_mov_b64_e32 v[240:241], v[80:81]
	s_nop 1
	v_permlane16_swap_b32 v240, v242
	v_permlane16_swap_b32 v241, v243
	v_lshl_add_u64 v[248:249], v[88:89], 0, v[230:231]
	global_store_dwordx4 v[248:249], v[240:243], off offset:256
	s_nop 1
	global_store_dwordx2 v[72:73], v[74:75], off offset:32
	v_mov_b64_e32 v[244:245], v[68:69]
	s_nop 1
	v_permlane16_swap_b32 v244, v246
	v_permlane16_swap_b32 v245, v247
	v_lshl_add_u64 v[248:249], v[72:73], 0, v[230:231]
	global_store_dwordx4 v[248:249], v[244:247], off offset:256
	s_nop 1
	v_mov_b64_e32 v[232:233], v[60:61]
	v_mov_b64_e32 v[234:235], v[56:57]
	s_nop 1
	v_permlane16_swap_b32 v232, v234
	v_permlane16_swap_b32 v233, v235
	v_lshl_add_u64 v[248:249], v[64:65], 0, v[230:231]
	global_store_dwordx4 v[248:249], v[232:235], off
	s_nop 1
	global_store_dwordx2 v[64:65], v[48:49], off offset:256
	global_store_dwordx2 v[40:41], v[42:43], off offset:32
	global_store_dwordx2 v[40:41], v[32:33], off offset:256
	global_store_dwordx2 v[24:25], v[26:27], off offset:32
	global_store_dwordx2 v[24:25], v[16:17], off offset:256
	global_store_dwordx2 v[8:9], v[10:11], off offset:32
	v_mov_b64_e32 v[232:233], v[4:5]
	v_mov_b64_e32 v[234:235], v[0:1]
	s_nop 1
	v_permlane16_swap_b32 v232, v234
	v_permlane16_swap_b32 v233, v235
	v_lshl_add_u64 v[248:249], v[8:9], 0, v[230:231]
	global_store_dwordx4 v[248:249], v[232:235], off offset:256
	s_nop 1
	s_cbranch_vccz .LBB0_147
	s_waitcnt vmcnt(0)
	s_cmpk_gt_u32 s20, 0xff
	s_mov_b32 s28, 0x8000
	s_movk_i32 s29, 0xc0
	s_mov_b32 s30, 0x800000
	s_movk_i32 s31, 0x7fff
	s_movk_i32 s33, 0x1800
	s_cbranch_scc1 .LBB0_154
	s_barrier

.LBB0_192:
	s_ashr_i32 s2, s4, 4
	s_ashr_i32 s3, s2, 31
	s_and_b32 s5, s0, 0xf00
	s_lshl_b64 s[6:7], s[2:3], 8
	s_add_u32 s6, s16, s6
	s_addc_u32 s7, s17, s7
	s_lshl_b64 s[8:9], s[2:3], 14
	v_mov_b32_e32 v10, v204
	s_add_u32 s8, s14, s8
	s_addc_u32 s9, s15, s9
	v_readfirstlane_b32 s10, v10
	s_ashr_i32 s11, s10, 6
	v_bfe_u32 v0, v10, 3, 3
	v_lshl_or_b32 v0, s11, 3, v0
	s_and_b32 s12, s11, 1
	v_add_u32_e32 v2, s5, v0
	v_and_b32_e32 v1, 7, v10
	s_lshl_b32 s13, s12, 2
	v_bfe_u32 v11, v10, 4, 2
	v_ashrrev_i32_e32 v3, 31, v2
	v_bitop3_b32 v1, s13, v1, v11 bitop3:0x36
	v_lshlrev_b64 v[2:3], 15, v[2:3]
	v_lshl_add_u64 v[2:3], s[6:7], 0, v[2:3]
	v_lshlrev_b32_e32 v188, 4, v1
	v_lshl_add_u64 v[2:3], v[2:3], 0, v[188:189]
	s_mov_b64 s[6:7], 0x200000
	v_lshl_add_u64 v[4:5], v[2:3], 0, s[6:7]
	s_mov_b64 s[6:7], 0x400000
	v_lshl_add_u64 v[6:7], v[2:3], 0, s[6:7]
	s_mov_b64 s[6:7], 0x600000
	v_ashrrev_i32_e32 v1, 31, v0
	v_lshl_add_u64 v[8:9], v[2:3], 0, s[6:7]
	v_lshlrev_b64 v[0:1], 8, v[0:1]
	s_lshl_b32 s6, s11, 10
	v_lshl_add_u64 v[0:1], s[8:9], 0, v[0:1]
	s_add_i32 s8, s6, 0
	s_mov_b32 m0, s8
	v_lshl_add_u64 v[0:1], v[0:1], 0, v[188:189]
	global_load_lds_dwordx4 v[2:3], off
	s_add_i32 m0, s8, 0x2000
	s_mov_b64 s[6:7], 0x200080
	global_load_lds_dwordx4 v[4:5], off
	s_add_i32 m0, s8, 0x4000
	v_lshl_add_u64 v[4:5], v[2:3], 0, s[92:93]
	global_load_lds_dwordx4 v[6:7], off
	s_add_i32 m0, s8, 0x6000
	s_nop 0
	global_load_lds_dwordx4 v[8:9], off
	s_add_i32 m0, s8, 0x8000
	s_nop 0
	global_load_lds_dwordx4 v[0:1], off
	s_add_i32 m0, s8, 0xc000
	v_lshl_add_u64 v[0:1], v[0:1], 0, s[92:93]
	global_load_lds_dwordx4 v[4:5], off
	v_lshl_add_u64 v[4:5], v[2:3], 0, s[6:7]
	s_add_i32 m0, s8, 0xe000
	s_mov_b64 s[6:7], 0x400080
	global_load_lds_dwordx4 v[4:5], off
	v_lshl_add_u64 v[4:5], v[2:3], 0, s[6:7]
	s_add_i32 m0, s8, 0x10000
	s_mov_b64 s[6:7], 0x600080
	global_load_lds_dwordx4 v[4:5], off
	v_lshl_add_u64 v[2:3], v[2:3], 0, s[6:7]
	s_add_i32 m0, s8, 0x12000
	s_lshr_b32 s6, s10, 1
	global_load_lds_dwordx4 v[2:3], off
	s_add_i32 m0, s8, 0x14000
	s_and_b32 s6, s6, 0x1ffffc0
	global_load_lds_dwordx4 v[0:1], off
	s_waitcnt vmcnt(5)
	v_bfe_u32 v1, v10, 1, 3
	s_waitcnt lgkmcnt(0)
	s_barrier
	v_and_b32_e32 v0, 15, v10
	v_xor_b32_e32 v1, v11, v1
	v_lshlrev_b32_e32 v60, 4, v1
	v_or_b32_e32 v1, s6, v0
	v_lshlrev_b32_e32 v0, 7, v0
	v_lshl_or_b32 v16, s12, 12, v0
	v_or_b32_e32 v61, 0x8000, v16
	v_xor_b32_e32 v62, 64, v60
	v_lshl_add_u32 v24, v1, 7, 0
	v_add_u32_e32 v25, 0, v16
	v_add_u32_e32 v63, v24, v60
	v_add_u32_e32 v20, v25, v60
	v_add_u32_e32 v44, v25, v62
	v_add_u32_e32 v68, v24, v62
	ds_read_b128 v[0:3], v63
	ds_read_b128 v[4:7], v63 offset:2048
	ds_read_b128 v[8:11], v63 offset:4096
	ds_read_b128 v[12:15], v63 offset:6144
	ds_read_b128 v[16:19], v20 offset:32768
	ds_read_b128 v[20:23], v20 offset:34816
	ds_read_b128 v[24:27], v68
	ds_read_b128 v[28:31], v68 offset:2048
	ds_read_b128 v[32:35], v68 offset:4096
	ds_read_b128 v[36:39], v68 offset:6144
	ds_read_b128 v[40:43], v44 offset:32768
	ds_read_b128 v[44:47], v44 offset:34816
	s_waitcnt lgkmcnt(0)
	v_mfma_f32_16x16x32_bf16 v[48:51], v[0:3], v[16:19], 0
	v_mfma_f32_16x16x32_bf16 v[0:3], v[0:3], v[20:23], 0
	v_mfma_f32_16x16x32_bf16 v[52:55], v[4:7], v[16:19], 0
	v_mfma_f32_16x16x32_bf16 v[4:7], v[4:7], v[20:23], 0
	v_mfma_f32_16x16x32_bf16 v[56:59], v[8:11], v[16:19], 0
	v_mfma_f32_16x16x32_bf16 v[8:11], v[8:11], v[20:23], 0
	v_mfma_f32_16x16x32_bf16 v[16:19], v[12:15], v[16:19], 0
	v_mfma_f32_16x16x32_bf16 v[12:15], v[12:15], v[20:23], 0
	v_mfma_f32_16x16x32_bf16 v[20:23], v[24:27], v[40:43], v[48:51]
	v_mfma_f32_16x16x32_bf16 v[0:3], v[24:27], v[44:47], v[0:3]
	v_mfma_f32_16x16x32_bf16 v[24:27], v[28:31], v[40:43], v[52:55]
	v_mfma_f32_16x16x32_bf16 v[4:7], v[28:31], v[44:47], v[4:7]
	v_mfma_f32_16x16x32_bf16 v[28:31], v[32:35], v[40:43], v[56:59]
	v_mfma_f32_16x16x32_bf16 v[8:11], v[32:35], v[44:47], v[8:11]
	v_mfma_f32_16x16x32_bf16 v[16:19], v[36:39], v[40:43], v[16:19]
	v_mfma_f32_16x16x32_bf16 v[12:15], v[36:39], v[44:47], v[12:15]
	s_waitcnt vmcnt(0)
	s_waitcnt lgkmcnt(0)
	s_barrier
	s_add_i32 s6, 0, 0xc000
	v_add3_u32 v52, s6, v60, v61
	v_add3_u32 v76, s6, v62, v61
	ds_read_b128 v[32:35], v63 offset:49152
	ds_read_b128 v[36:39], v63 offset:51200
	ds_read_b128 v[40:43], v63 offset:53248
	ds_read_b128 v[44:47], v63 offset:55296
	ds_read_b128 v[48:51], v52
	ds_read_b128 v[52:55], v52 offset:2048
	ds_read_b128 v[56:59], v68 offset:49152
	ds_read_b128 v[60:63], v68 offset:51200
	ds_read_b128 v[64:67], v68 offset:53248
	ds_read_b128 v[68:71], v68 offset:55296
	ds_read_b128 v[72:75], v76
	ds_read_b128 v[76:79], v76 offset:2048
	s_waitcnt lgkmcnt(0)
	v_mfma_f32_16x16x32_bf16 v[20:23], v[32:35], v[48:51], v[20:23]
	v_mfma_f32_16x16x32_bf16 v[0:3], v[32:35], v[52:55], v[0:3]
	v_mfma_f32_16x16x32_bf16 v[24:27], v[36:39], v[48:51], v[24:27]
	v_mfma_f32_16x16x32_bf16 v[4:7], v[36:39], v[52:55], v[4:7]
	v_mfma_f32_16x16x32_bf16 v[28:31], v[40:43], v[48:51], v[28:31]
	v_mfma_f32_16x16x32_bf16 v[8:11], v[40:43], v[52:55], v[8:11]
	v_mfma_f32_16x16x32_bf16 v[16:19], v[44:47], v[48:51], v[16:19]
	v_mfma_f32_16x16x32_bf16 v[12:15], v[44:47], v[52:55], v[12:15]
	v_mfma_f32_16x16x32_bf16 v[20:23], v[56:59], v[72:75], v[20:23]
	v_mfma_f32_16x16x32_bf16 v[0:3], v[56:59], v[76:79], v[0:3]
	v_mfma_f32_16x16x32_bf16 v[24:27], v[60:63], v[72:75], v[24:27]
	v_mfma_f32_16x16x32_bf16 v[4:7], v[60:63], v[76:79], v[4:7]
	v_mfma_f32_16x16x32_bf16 v[28:31], v[64:67], v[72:75], v[28:31]
	v_mfma_f32_16x16x32_bf16 v[8:11], v[64:67], v[76:79], v[8:11]
	v_mfma_f32_16x16x32_bf16 v[16:19], v[68:71], v[72:75], v[16:19]
	v_mfma_f32_16x16x32_bf16 v[12:15], v[68:71], v[76:79], v[12:15]
	s_waitcnt vmcnt(0)
	v_mov_b32_e32 v32, v204
	s_waitcnt lgkmcnt(0)
	s_barrier
	v_cvt_pk_bf16_f32 v20, v20, v21
	v_ashrrev_i32_e32 v33, 1, v32
	v_and_b32_e32 v34, 0xffffffc0, v33
	v_lshrrev_b32_e32 v35, 2, v32
	v_lshrrev_b32_e32 v36, 1, v32
	v_and_b32_e32 v32, 15, v32
	v_add_u32_e32 v34, s5, v34
	v_and_or_b32 v36, v36, 32, v32
	v_and_b32_e32 v35, 12, v35
	v_ashrrev_i32_e32 v32, 10, v34
	v_lshlrev_b32_e32 v188, 7, v36
	v_and_or_b32 v37, v33, s29, v35
	v_ashrrev_i32_e32 v33, 31, v32
	v_cvt_pk_bf16_f32 v21, v22, v23
	v_lshl_add_u64 v[22:23], v[188:189], 0, s[2:3]
	v_or_b32_e32 v188, 0x800, v188
	v_lshlrev_b64 v[32:33], 13, v[32:33]
	v_cvt_pk_bf16_f32 v0, v0, v1
	v_cvt_pk_bf16_f32 v1, v2, v3
	v_lshl_add_u64 v[2:3], v[188:189], 0, s[2:3]
	v_lshl_add_u64 v[2:3], v[2:3], 0, v[32:33]
	v_and_b32_e32 v34, 0x300, v34
	v_lshl_add_u64 v[22:23], v[22:23], 0, v[32:33]
	v_lshlrev_b64 v[2:3], 11, v[2:3]
	v_lshlrev_b64 v[22:23], 11, v[22:23]
	v_lshlrev_b32_e32 v34, 1, v34
	v_mov_b32_e32 v35, v189
	v_lshl_add_u64 v[2:3], s[88:89], 0, v[2:3]
	v_lshl_add_u64 v[22:23], s[88:89], 0, v[22:23]
	v_lshlrev_b32_e32 v36, 1, v37
	v_mov_b32_e32 v37, v189
	v_lshl_add_u64 v[2:3], v[2:3], 0, v[34:35]
	v_lshl_add_u64 v[22:23], v[22:23], 0, v[34:35]
	v_lshl_add_u64 v[2:3], v[2:3], 0, v[36:37]
	v_lshl_add_u64 v[22:23], v[22:23], 0, v[36:37]
	v_and_b32_e32 v230, 16, v204
	v_lshrrev_b32_e32 v231, 1, v230
	v_add_u32_e32 v230, v230, v231
	v_mov_b32_e32 v231, v189
	v_lshl_add_u64 v[2:3], v[2:3], 0, v[230:231]
	v_lshl_add_u64 v[22:23], v[22:23], 0, v[230:231]
	v_mov_b64_e32 v[232:233], v[0:1]
	v_cvt_pk_bf16_f32 v234, v4, v5
	v_cvt_pk_bf16_f32 v235, v6, v7
	s_nop 1
	v_permlane16_swap_b32 v232, v234
	v_permlane16_swap_b32 v233, v235
	global_store_dwordx4 v[2:3], v[232:235], off
	v_cvt_pk_bf16_f32 v236, v8, v9
	v_cvt_pk_bf16_f32 v237, v10, v11
	v_cvt_pk_bf16_f32 v238, v12, v13
	v_cvt_pk_bf16_f32 v239, v14, v15
	s_nop 1
	v_permlane16_swap_b32 v236, v238
	v_permlane16_swap_b32 v237, v239
	global_store_dwordx4 v[2:3], v[236:239], off offset:64
	s_add_i32 s4, s4, s96
	s_add_i32 s0, s0, s74
	v_mov_b64_e32 v[232:233], v[20:21]
	v_cvt_pk_bf16_f32 v234, v24, v25
	v_cvt_pk_bf16_f32 v235, v26, v27
	s_nop 1
	v_permlane16_swap_b32 v232, v234
	v_permlane16_swap_b32 v233, v235
	global_store_dwordx4 v[22:23], v[232:235], off
	v_cvt_pk_bf16_f32 v236, v28, v29
	v_cvt_pk_bf16_f32 v237, v30, v31
	v_cvt_pk_bf16_f32 v238, v16, v17
	v_cvt_pk_bf16_f32 v239, v18, v19
	s_nop 1
	v_permlane16_swap_b32 v236, v238
	v_permlane16_swap_b32 v237, v239
	s_cmpk_gt_i32 s4, 0x7ff
	global_store_dwordx4 v[22:23], v[236:239], off offset:64
	s_cbranch_scc0 .LBB0_192

.LBB0_200:
	s_ashr_i32 s7, s6, 31
	s_lshl_b64 s[12:13], s[6:7], 17
	v_readlane_b32 s14, v253, 52
	v_readlane_b32 s15, v253, 53
	s_add_u32 s12, s14, s12
	s_addc_u32 s13, s15, s13
	s_and_b64 s[14:15], s[16:17], exec
	s_cselect_b32 s19, s13, s21
	s_cselect_b32 s18, s12, s20
	s_ashr_i32 s9, s8, 31
	s_lshl_b64 s[14:15], s[8:9], 17
	s_add_u32 s14, s88, s14
	s_addc_u32 s15, s89, s15
	s_and_b64 s[16:17], s[16:17], exec
	s_cselect_b32 s17, s15, s23
	s_cselect_b32 s16, s14, s22
	s_add_i32 s36, 0, 0x10000
	v_add_u32_e32 v206, s36, v12
	ds_read_b128 v[14:17], v206
	ds_read_b128 v[18:21], v206 offset:1024
	ds_read_b128 v[22:25], v206 offset:2048
	ds_read_b128 v[26:29], v206 offset:3072
	s_add_u32 s38, s20, 0x10080
	s_addc_u32 s39, s21, 0
	s_add_i32 s37, s25, 0xc000
	v_lshl_add_u64 v[62:63], s[38:39], 0, v[2:3]
	s_mov_b32 m0, s37
	s_add_i32 s7, s25, 0xe000
	ds_read_b128 v[30:33], v13
	ds_read_b128 v[34:37], v13 offset:1024
	ds_read_b128 v[38:41], v13 offset:2048
	ds_read_b128 v[42:45], v13 offset:3072
	ds_read_b128 v[46:49], v13 offset:4096
	ds_read_b128 v[50:53], v13 offset:5120
	ds_read_b128 v[54:57], v13 offset:6144
	ds_read_b128 v[58:61], v13 offset:7168
	global_load_lds_dwordx4 v[62:63], off
	v_lshl_add_u64 v[62:63], s[38:39], 0, v[0:1]
	s_mov_b32 m0, s7
	s_nop 0
	global_load_lds_dwordx4 v[62:63], off
	s_waitcnt lgkmcnt(8)
	s_barrier
	s_waitcnt lgkmcnt(0)
	s_setprio 1
	s_waitcnt lgkmcnt(0)
	v_mfma_f32_16x16x32_bf16 v[62:65], v[14:17], v[30:33], 0
	v_mfma_f32_16x16x32_bf16 v[66:69], v[22:25], v[30:33], 0
	v_mfma_f32_16x16x32_bf16 v[70:73], v[14:17], v[38:41], 0
	v_mfma_f32_16x16x32_bf16 v[74:77], v[22:25], v[38:41], 0
	v_mfma_f32_16x16x32_bf16 v[78:81], v[14:17], v[46:49], 0
	v_mfma_f32_16x16x32_bf16 v[82:85], v[22:25], v[46:49], 0
	v_mfma_f32_16x16x32_bf16 v[86:89], v[14:17], v[54:57], 0
	v_mfma_f32_16x16x32_bf16 v[90:93], v[22:25], v[54:57], 0
	v_mfma_f32_16x16x32_bf16 v[62:65], v[18:21], v[34:37], v[62:65]
	v_mfma_f32_16x16x32_bf16 v[66:69], v[26:29], v[34:37], v[66:69]
	v_mfma_f32_16x16x32_bf16 v[70:73], v[18:21], v[42:45], v[70:73]
	v_mfma_f32_16x16x32_bf16 v[74:77], v[26:29], v[42:45], v[74:77]
	v_mfma_f32_16x16x32_bf16 v[78:81], v[18:21], v[50:53], v[78:81]
	v_mfma_f32_16x16x32_bf16 v[82:85], v[26:29], v[50:53], v[82:85]
	v_mfma_f32_16x16x32_bf16 v[86:89], v[18:21], v[58:61], v[86:89]
	v_mfma_f32_16x16x32_bf16 v[90:93], v[26:29], v[58:61], v[90:93]
	s_setprio 0
	s_barrier
	s_add_i32 s38, 0, 0x14000
	v_lshl_add_u64 v[186:187], s[22:23], 0, v[2:3]
	s_add_i32 s36, s36, s24
	v_add_u32_e32 v215, s38, v12
	v_lshl_add_u64 v[110:111], v[186:187], 0, s[40:41]
	s_mov_b32 m0, s36
	v_lshl_add_u64 v[202:203], s[22:23], 0, v[0:1]
	s_add_i32 s9, s36, 0x2000
	ds_read_b128 v[94:97], v215
	ds_read_b128 v[98:101], v215 offset:1024
	ds_read_b128 v[102:105], v215 offset:2048
	ds_read_b128 v[106:109], v215 offset:3072
	global_load_lds_dwordx4 v[110:111], off
	v_lshl_add_u64 v[110:111], v[202:203], 0, s[40:41]
	s_mov_b32 m0, s9
	s_nop 0
	global_load_lds_dwordx4 v[110:111], off
	s_barrier
	s_waitcnt lgkmcnt(0)
	s_setprio 1
	s_waitcnt lgkmcnt(0)
	v_mfma_f32_16x16x32_bf16 v[110:113], v[94:97], v[30:33], 0
	v_mfma_f32_16x16x32_bf16 v[30:33], v[102:105], v[30:33], 0
	v_mfma_f32_16x16x32_bf16 v[110:113], v[98:101], v[34:37], v[110:113]
	v_mfma_f32_16x16x32_bf16 v[30:33], v[106:109], v[34:37], v[30:33]
	v_mfma_f32_16x16x32_bf16 v[34:37], v[94:97], v[38:41], 0
	v_mfma_f32_16x16x32_bf16 v[38:41], v[102:105], v[38:41], 0
	v_mfma_f32_16x16x32_bf16 v[34:37], v[98:101], v[42:45], v[34:37]
	v_mfma_f32_16x16x32_bf16 v[38:41], v[106:109], v[42:45], v[38:41]
	v_mfma_f32_16x16x32_bf16 v[42:45], v[94:97], v[46:49], 0
	v_mfma_f32_16x16x32_bf16 v[46:49], v[102:105], v[46:49], 0
	v_mfma_f32_16x16x32_bf16 v[42:45], v[98:101], v[50:53], v[42:45]
	v_mfma_f32_16x16x32_bf16 v[46:49], v[106:109], v[50:53], v[46:49]
	v_mfma_f32_16x16x32_bf16 v[50:53], v[94:97], v[54:57], 0
	v_mfma_f32_16x16x32_bf16 v[54:57], v[102:105], v[54:57], 0
	v_mfma_f32_16x16x32_bf16 v[50:53], v[98:101], v[58:61], v[50:53]
	v_mfma_f32_16x16x32_bf16 v[54:57], v[106:109], v[58:61], v[54:57]
	s_setprio 0
	v_lshl_add_u64 v[224:225], s[20:21], 0, v[2:3]
	s_mov_b32 m0, s25
	v_lshl_add_u64 v[142:143], v[224:225], 0, s[40:41]
	v_lshl_add_u64 v[226:227], s[20:21], 0, v[0:1]
	s_barrier
	ds_read_b128 v[58:61], v13 offset:16384
	ds_read_b128 v[114:117], v13 offset:17408
	ds_read_b128 v[118:121], v13 offset:18432
	ds_read_b128 v[122:125], v13 offset:19456
	ds_read_b128 v[126:129], v13 offset:20480
	ds_read_b128 v[130:133], v13 offset:21504
	ds_read_b128 v[134:137], v13 offset:22528
	ds_read_b128 v[138:141], v13 offset:23552
	global_load_lds_dwordx4 v[142:143], off
	v_lshl_add_u64 v[142:143], v[226:227], 0, s[40:41]
	s_mov_b32 m0, s26
	s_nop 0
	global_load_lds_dwordx4 v[142:143], off
	s_barrier
	s_waitcnt lgkmcnt(0)
	s_setprio 1
	s_waitcnt lgkmcnt(0)
	v_mfma_f32_16x16x32_bf16 v[142:145], v[14:17], v[58:61], 0
	v_mfma_f32_16x16x32_bf16 v[150:153], v[14:17], v[118:121], 0
	v_mfma_f32_16x16x32_bf16 v[158:161], v[14:17], v[126:129], 0
	v_mfma_f32_16x16x32_bf16 v[14:17], v[14:17], v[134:137], 0
	v_mfma_f32_16x16x32_bf16 v[142:145], v[18:21], v[114:117], v[142:145]
	v_mfma_f32_16x16x32_bf16 v[146:149], v[22:25], v[58:61], 0
	v_mfma_f32_16x16x32_bf16 v[150:153], v[18:21], v[122:125], v[150:153]
	v_mfma_f32_16x16x32_bf16 v[154:157], v[22:25], v[118:121], 0
	v_mfma_f32_16x16x32_bf16 v[158:161], v[18:21], v[130:133], v[158:161]
	v_mfma_f32_16x16x32_bf16 v[162:165], v[22:25], v[126:129], 0
	v_mfma_f32_16x16x32_bf16 v[14:17], v[18:21], v[138:141], v[14:17]
	v_mfma_f32_16x16x32_bf16 v[18:21], v[22:25], v[134:137], 0
	v_mfma_f32_16x16x32_bf16 v[146:149], v[26:29], v[114:117], v[146:149]
	v_mfma_f32_16x16x32_bf16 v[154:157], v[26:29], v[122:125], v[154:157]
	v_mfma_f32_16x16x32_bf16 v[162:165], v[26:29], v[130:133], v[162:165]
	v_mfma_f32_16x16x32_bf16 v[18:21], v[26:29], v[138:141], v[18:21]
	s_setprio 0
	s_barrier
	s_add_u32 s40, s22, 0x10100
	s_addc_u32 s41, s23, 0
	s_add_i32 s38, s38, s24
	v_lshl_add_u64 v[22:23], s[40:41], 0, v[2:3]
	s_mov_b32 m0, s38
	s_add_i32 s35, s38, 0x2000
	global_load_lds_dwordx4 v[22:23], off
	v_lshl_add_u64 v[22:23], s[40:41], 0, v[0:1]
	s_mov_b32 m0, s35
	s_nop 0
	global_load_lds_dwordx4 v[22:23], off
	s_waitcnt vmcnt(6)
	s_barrier
	s_setprio 1
	v_mfma_f32_16x16x32_bf16 v[22:25], v[94:97], v[58:61], 0
	v_mfma_f32_16x16x32_bf16 v[26:29], v[102:105], v[58:61], 0
	v_mfma_f32_16x16x32_bf16 v[22:25], v[98:101], v[114:117], v[22:25]
	v_mfma_f32_16x16x32_bf16 v[26:29], v[106:109], v[114:117], v[26:29]
	v_mfma_f32_16x16x32_bf16 v[58:61], v[94:97], v[118:121], 0
	v_mfma_f32_16x16x32_bf16 v[114:117], v[102:105], v[118:121], 0
	v_mfma_f32_16x16x32_bf16 v[118:121], v[94:97], v[126:129], 0
	v_mfma_f32_16x16x32_bf16 v[94:97], v[94:97], v[134:137], 0
	v_mfma_f32_16x16x32_bf16 v[58:61], v[98:101], v[122:125], v[58:61]
	v_mfma_f32_16x16x32_bf16 v[114:117], v[106:109], v[122:125], v[114:117]
	v_mfma_f32_16x16x32_bf16 v[118:121], v[98:101], v[130:133], v[118:121]
	v_mfma_f32_16x16x32_bf16 v[122:125], v[102:105], v[126:129], 0
	v_mfma_f32_16x16x32_bf16 v[94:97], v[98:101], v[138:141], v[94:97]
	v_mfma_f32_16x16x32_bf16 v[98:101], v[102:105], v[134:137], 0
	v_mfma_f32_16x16x32_bf16 v[122:125], v[106:109], v[130:133], v[122:125]
	v_mfma_f32_16x16x32_bf16 v[98:101], v[106:109], v[138:141], v[98:101]
	s_setprio 0
	s_add_i32 s39, 0, 0x18000
	v_add_u32_e32 v228, s39, v12
	s_barrier
	ds_read_b128 v[102:105], v228
	ds_read_b128 v[106:109], v228 offset:1024
	ds_read_b128 v[126:129], v228 offset:2048
	ds_read_b128 v[130:133], v228 offset:3072
	s_add_u32 s40, s20, 0x10100
	s_addc_u32 s41, s21, 0
	s_mov_b32 m0, s27
	v_lshl_add_u64 v[194:195], s[40:41], 0, v[2:3]
	ds_read_b128 v[134:137], v13 offset:32768
	ds_read_b128 v[138:141], v13 offset:33792
	ds_read_b128 v[166:169], v13 offset:34816
	ds_read_b128 v[170:173], v13 offset:35840
	ds_read_b128 v[174:177], v13 offset:36864
	ds_read_b128 v[178:181], v13 offset:37888
	ds_read_b128 v[182:185], v13 offset:38912
	ds_read_b128 v[190:193], v13 offset:39936
	global_load_lds_dwordx4 v[194:195], off
	v_lshl_add_u64 v[194:195], s[40:41], 0, v[0:1]
	s_mov_b32 m0, s28
	s_nop 0
	global_load_lds_dwordx4 v[194:195], off
	s_waitcnt lgkmcnt(8)
	s_barrier
	s_waitcnt lgkmcnt(0)
	s_setprio 1
	s_waitcnt lgkmcnt(0)
	v_mfma_f32_16x16x32_bf16 v[62:65], v[102:105], v[134:137], v[62:65]
	v_mfma_f32_16x16x32_bf16 v[66:69], v[126:129], v[134:137], v[66:69]
	v_mfma_f32_16x16x32_bf16 v[70:73], v[102:105], v[166:169], v[70:73]
	v_mfma_f32_16x16x32_bf16 v[74:77], v[126:129], v[166:169], v[74:77]
	v_mfma_f32_16x16x32_bf16 v[78:81], v[102:105], v[174:177], v[78:81]
	v_mfma_f32_16x16x32_bf16 v[82:85], v[126:129], v[174:177], v[82:85]
	v_mfma_f32_16x16x32_bf16 v[86:89], v[102:105], v[182:185], v[86:89]
	v_mfma_f32_16x16x32_bf16 v[90:93], v[126:129], v[182:185], v[90:93]
	v_mfma_f32_16x16x32_bf16 v[62:65], v[106:109], v[138:141], v[62:65]
	v_mfma_f32_16x16x32_bf16 v[66:69], v[130:133], v[138:141], v[66:69]
	v_mfma_f32_16x16x32_bf16 v[70:73], v[106:109], v[170:173], v[70:73]
	v_mfma_f32_16x16x32_bf16 v[74:77], v[130:133], v[170:173], v[74:77]
	v_mfma_f32_16x16x32_bf16 v[78:81], v[106:109], v[178:181], v[78:81]
	v_mfma_f32_16x16x32_bf16 v[82:85], v[130:133], v[178:181], v[82:85]
	v_mfma_f32_16x16x32_bf16 v[86:89], v[106:109], v[190:193], v[86:89]
	v_mfma_f32_16x16x32_bf16 v[90:93], v[130:133], v[190:193], v[90:93]
	s_setprio 0
	s_barrier
	s_add_i32 s41, 0, 0x1c000
	s_add_i32 s40, s39, s24
	v_add_u32_e32 v229, s41, v12
	v_lshl_add_u64 v[186:187], v[186:187], 0, s[42:43]
	s_mov_b32 m0, s40
	s_add_i32 s39, s40, 0x2000
	ds_read_b128 v[194:197], v229
	ds_read_b128 v[198:201], v229 offset:1024
	ds_read_b128 v[216:219], v229 offset:2048
	ds_read_b128 v[220:223], v229 offset:3072
	global_load_lds_dwordx4 v[186:187], off
	v_lshl_add_u64 v[186:187], v[202:203], 0, s[42:43]
	s_mov_b32 m0, s39
	s_nop 0
	global_load_lds_dwordx4 v[186:187], off
	s_barrier
	s_waitcnt lgkmcnt(0)
	s_setprio 1
	s_waitcnt lgkmcnt(0)
	v_mfma_f32_16x16x32_bf16 v[110:113], v[194:197], v[134:137], v[110:113]
	v_mfma_f32_16x16x32_bf16 v[30:33], v[216:219], v[134:137], v[30:33]
	v_mfma_f32_16x16x32_bf16 v[34:37], v[194:197], v[166:169], v[34:37]
	v_mfma_f32_16x16x32_bf16 v[38:41], v[216:219], v[166:169], v[38:41]
	v_mfma_f32_16x16x32_bf16 v[42:45], v[194:197], v[174:177], v[42:45]
	v_mfma_f32_16x16x32_bf16 v[46:49], v[216:219], v[174:177], v[46:49]
	v_mfma_f32_16x16x32_bf16 v[50:53], v[194:197], v[182:185], v[50:53]
	v_mfma_f32_16x16x32_bf16 v[54:57], v[216:219], v[182:185], v[54:57]
	v_mfma_f32_16x16x32_bf16 v[110:113], v[198:201], v[138:141], v[110:113]
	v_mfma_f32_16x16x32_bf16 v[30:33], v[220:223], v[138:141], v[30:33]
	v_mfma_f32_16x16x32_bf16 v[34:37], v[198:201], v[170:173], v[34:37]
	v_mfma_f32_16x16x32_bf16 v[38:41], v[220:223], v[170:173], v[38:41]
	v_mfma_f32_16x16x32_bf16 v[42:45], v[198:201], v[178:181], v[42:45]
	v_mfma_f32_16x16x32_bf16 v[46:49], v[220:223], v[178:181], v[46:49]
	v_mfma_f32_16x16x32_bf16 v[50:53], v[198:201], v[190:193], v[50:53]
	v_mfma_f32_16x16x32_bf16 v[54:57], v[220:223], v[190:193], v[54:57]
	s_setprio 0
	s_mov_b32 m0, s30
	v_lshl_add_u64 v[186:187], v[224:225], 0, s[42:43]
	s_barrier
	ds_read_b128 v[134:137], v13 offset:49152
	ds_read_b128 v[138:141], v13 offset:50176
	ds_read_b128 v[166:169], v13 offset:51200
	ds_read_b128 v[170:173], v13 offset:52224
	ds_read_b128 v[174:177], v13 offset:53248
	ds_read_b128 v[178:181], v13 offset:54272
	ds_read_b128 v[182:185], v13 offset:55296
	ds_read_b128 v[190:193], v13 offset:56320
	global_load_lds_dwordx4 v[186:187], off
	v_lshl_add_u64 v[186:187], v[226:227], 0, s[42:43]
	s_mov_b32 m0, s31
	s_nop 0
	global_load_lds_dwordx4 v[186:187], off
	s_barrier
	s_waitcnt lgkmcnt(0)
	s_setprio 1
	s_waitcnt lgkmcnt(0)
	v_mfma_f32_16x16x32_bf16 v[142:145], v[102:105], v[134:137], v[142:145]
	v_mfma_f32_16x16x32_bf16 v[146:149], v[126:129], v[134:137], v[146:149]
	v_mfma_f32_16x16x32_bf16 v[150:153], v[102:105], v[166:169], v[150:153]
	v_mfma_f32_16x16x32_bf16 v[154:157], v[126:129], v[166:169], v[154:157]
	v_mfma_f32_16x16x32_bf16 v[158:161], v[102:105], v[174:177], v[158:161]
	v_mfma_f32_16x16x32_bf16 v[162:165], v[126:129], v[174:177], v[162:165]
	v_mfma_f32_16x16x32_bf16 v[14:17], v[102:105], v[182:185], v[14:17]
	v_mfma_f32_16x16x32_bf16 v[18:21], v[126:129], v[182:185], v[18:21]
	v_mfma_f32_16x16x32_bf16 v[142:145], v[106:109], v[138:141], v[142:145]
	v_mfma_f32_16x16x32_bf16 v[146:149], v[130:133], v[138:141], v[146:149]
	v_mfma_f32_16x16x32_bf16 v[150:153], v[106:109], v[170:173], v[150:153]
	v_mfma_f32_16x16x32_bf16 v[154:157], v[130:133], v[170:173], v[154:157]
	v_mfma_f32_16x16x32_bf16 v[158:161], v[106:109], v[178:181], v[158:161]
	v_mfma_f32_16x16x32_bf16 v[162:165], v[130:133], v[178:181], v[162:165]
	v_mfma_f32_16x16x32_bf16 v[14:17], v[106:109], v[190:193], v[14:17]
	v_mfma_f32_16x16x32_bf16 v[18:21], v[130:133], v[190:193], v[18:21]
	s_setprio 0
	s_barrier
	s_add_u32 s42, s22, 0x10180
	s_addc_u32 s43, s23, 0
	s_add_i32 s23, s41, s24
	v_lshl_add_u64 v[102:103], s[42:43], 0, v[2:3]
	s_mov_b32 m0, s23
	s_add_i32 s22, s23, 0x2000
	global_load_lds_dwordx4 v[102:103], off
	v_lshl_add_u64 v[102:103], s[42:43], 0, v[0:1]
	s_mov_b32 m0, s22
	s_nop 0
	global_load_lds_dwordx4 v[102:103], off
	s_waitcnt vmcnt(6)
	s_barrier
	s_setprio 1
	v_mfma_f32_16x16x32_bf16 v[22:25], v[194:197], v[134:137], v[22:25]
	v_mfma_f32_16x16x32_bf16 v[26:29], v[216:219], v[134:137], v[26:29]
	v_mfma_f32_16x16x32_bf16 v[58:61], v[194:197], v[166:169], v[58:61]
	v_mfma_f32_16x16x32_bf16 v[102:105], v[216:219], v[166:169], v[114:117]
	v_mfma_f32_16x16x32_bf16 v[106:109], v[194:197], v[174:177], v[118:121]
	v_mfma_f32_16x16x32_bf16 v[114:117], v[216:219], v[174:177], v[122:125]
	v_mfma_f32_16x16x32_bf16 v[94:97], v[194:197], v[182:185], v[94:97]
	v_mfma_f32_16x16x32_bf16 v[98:101], v[216:219], v[182:185], v[98:101]
	v_mfma_f32_16x16x32_bf16 v[22:25], v[198:201], v[138:141], v[22:25]
	v_mfma_f32_16x16x32_bf16 v[26:29], v[220:223], v[138:141], v[26:29]
	v_mfma_f32_16x16x32_bf16 v[58:61], v[198:201], v[170:173], v[58:61]
	v_mfma_f32_16x16x32_bf16 v[102:105], v[220:223], v[170:173], v[102:105]
	v_mfma_f32_16x16x32_bf16 v[106:109], v[198:201], v[178:181], v[106:109]
	v_mfma_f32_16x16x32_bf16 v[114:117], v[220:223], v[178:181], v[114:117]
	v_mfma_f32_16x16x32_bf16 v[94:97], v[198:201], v[190:193], v[94:97]
	v_mfma_f32_16x16x32_bf16 v[98:101], v[220:223], v[190:193], v[98:101]
	s_setprio 0
	s_barrier
	ds_read_b128 v[118:121], v206
	ds_read_b128 v[122:125], v206 offset:1024
	ds_read_b128 v[126:129], v206 offset:2048
	ds_read_b128 v[130:133], v206 offset:3072
	s_add_u32 s20, s20, 0x10180
	s_addc_u32 s21, s21, 0
	s_mov_b32 m0, s37
	v_lshl_add_u64 v[186:187], s[20:21], 0, v[2:3]
	ds_read_b128 v[134:137], v13
	ds_read_b128 v[138:141], v13 offset:1024
	ds_read_b128 v[166:169], v13 offset:2048
	ds_read_b128 v[170:173], v13 offset:3072
	ds_read_b128 v[174:177], v13 offset:4096
	ds_read_b128 v[178:181], v13 offset:5120
	ds_read_b128 v[182:185], v13 offset:6144
	ds_read_b128 v[190:193], v13 offset:7168
	global_load_lds_dwordx4 v[186:187], off
	v_lshl_add_u64 v[186:187], s[20:21], 0, v[0:1]
	s_mov_b32 m0, s7
	s_nop 0
	global_load_lds_dwordx4 v[186:187], off
	s_waitcnt lgkmcnt(8)
	s_barrier
	s_waitcnt lgkmcnt(0)
	s_setprio 1
	s_waitcnt lgkmcnt(0)
	v_mfma_f32_16x16x32_bf16 v[62:65], v[118:121], v[134:137], v[62:65]
	v_mfma_f32_16x16x32_bf16 v[66:69], v[126:129], v[134:137], v[66:69]
	v_mfma_f32_16x16x32_bf16 v[70:73], v[118:121], v[166:169], v[70:73]
	v_mfma_f32_16x16x32_bf16 v[74:77], v[126:129], v[166:169], v[74:77]
	v_mfma_f32_16x16x32_bf16 v[78:81], v[118:121], v[174:177], v[78:81]
	v_mfma_f32_16x16x32_bf16 v[82:85], v[126:129], v[174:177], v[82:85]
	v_mfma_f32_16x16x32_bf16 v[86:89], v[118:121], v[182:185], v[86:89]
	v_mfma_f32_16x16x32_bf16 v[90:93], v[126:129], v[182:185], v[90:93]
	v_mfma_f32_16x16x32_bf16 v[62:65], v[122:125], v[138:141], v[62:65]
	v_mfma_f32_16x16x32_bf16 v[66:69], v[130:133], v[138:141], v[66:69]
	v_mfma_f32_16x16x32_bf16 v[70:73], v[122:125], v[170:173], v[70:73]
	v_mfma_f32_16x16x32_bf16 v[74:77], v[130:133], v[170:173], v[74:77]
	v_mfma_f32_16x16x32_bf16 v[78:81], v[122:125], v[178:181], v[78:81]
	v_mfma_f32_16x16x32_bf16 v[82:85], v[130:133], v[178:181], v[82:85]
	v_mfma_f32_16x16x32_bf16 v[86:89], v[122:125], v[190:193], v[86:89]
	v_mfma_f32_16x16x32_bf16 v[90:93], v[130:133], v[190:193], v[90:93]
	s_setprio 0
	s_barrier
	s_mov_b32 m0, s36
	v_lshl_add_u64 v[186:187], s[16:17], 0, v[2:3]
	ds_read_b128 v[194:197], v215
	ds_read_b128 v[198:201], v215 offset:1024
	ds_read_b128 v[216:219], v215 offset:2048
	ds_read_b128 v[220:223], v215 offset:3072
	global_load_lds_dwordx4 v[186:187], off
	v_lshl_add_u64 v[202:203], s[16:17], 0, v[0:1]
	s_mov_b32 m0, s9
	s_nop 0
	global_load_lds_dwordx4 v[202:203], off
	s_barrier
	s_waitcnt lgkmcnt(0)
	s_setprio 1
	s_waitcnt lgkmcnt(0)
	v_mfma_f32_16x16x32_bf16 v[110:113], v[194:197], v[134:137], v[110:113]
	v_mfma_f32_16x16x32_bf16 v[30:33], v[216:219], v[134:137], v[30:33]
	v_mfma_f32_16x16x32_bf16 v[34:37], v[194:197], v[166:169], v[34:37]
	v_mfma_f32_16x16x32_bf16 v[38:41], v[216:219], v[166:169], v[38:41]
	v_mfma_f32_16x16x32_bf16 v[42:45], v[194:197], v[174:177], v[42:45]
	v_mfma_f32_16x16x32_bf16 v[46:49], v[216:219], v[174:177], v[46:49]
	v_mfma_f32_16x16x32_bf16 v[50:53], v[194:197], v[182:185], v[50:53]
	v_mfma_f32_16x16x32_bf16 v[54:57], v[216:219], v[182:185], v[54:57]
	v_mfma_f32_16x16x32_bf16 v[110:113], v[198:201], v[138:141], v[110:113]
	v_mfma_f32_16x16x32_bf16 v[30:33], v[220:223], v[138:141], v[30:33]
	v_mfma_f32_16x16x32_bf16 v[34:37], v[198:201], v[170:173], v[34:37]
	v_mfma_f32_16x16x32_bf16 v[38:41], v[220:223], v[170:173], v[38:41]
	v_mfma_f32_16x16x32_bf16 v[42:45], v[198:201], v[178:181], v[42:45]
	v_mfma_f32_16x16x32_bf16 v[46:49], v[220:223], v[178:181], v[46:49]
	v_mfma_f32_16x16x32_bf16 v[50:53], v[198:201], v[190:193], v[50:53]
	v_mfma_f32_16x16x32_bf16 v[54:57], v[220:223], v[190:193], v[54:57]
	s_setprio 0
	s_mov_b32 m0, s25
	v_lshl_add_u64 v[224:225], s[18:19], 0, v[2:3]
	s_barrier
	ds_read_b128 v[134:137], v13 offset:16384
	ds_read_b128 v[138:141], v13 offset:17408
	ds_read_b128 v[166:169], v13 offset:18432
	ds_read_b128 v[170:173], v13 offset:19456
	ds_read_b128 v[174:177], v13 offset:20480
	ds_read_b128 v[178:181], v13 offset:21504
	ds_read_b128 v[182:185], v13 offset:22528
	ds_read_b128 v[190:193], v13 offset:23552
	global_load_lds_dwordx4 v[224:225], off
	v_lshl_add_u64 v[226:227], s[18:19], 0, v[0:1]
	s_mov_b32 m0, s26
	s_nop 0
	global_load_lds_dwordx4 v[226:227], off
	s_barrier
	s_waitcnt lgkmcnt(0)
	s_setprio 1
	s_waitcnt lgkmcnt(0)
	v_mfma_f32_16x16x32_bf16 v[142:145], v[118:121], v[134:137], v[142:145]
	v_mfma_f32_16x16x32_bf16 v[146:149], v[126:129], v[134:137], v[146:149]
	v_mfma_f32_16x16x32_bf16 v[150:153], v[118:121], v[166:169], v[150:153]
	v_mfma_f32_16x16x32_bf16 v[154:157], v[126:129], v[166:169], v[154:157]
	v_mfma_f32_16x16x32_bf16 v[158:161], v[118:121], v[174:177], v[158:161]
	v_mfma_f32_16x16x32_bf16 v[162:165], v[126:129], v[174:177], v[162:165]
	v_mfma_f32_16x16x32_bf16 v[14:17], v[118:121], v[182:185], v[14:17]
	v_mfma_f32_16x16x32_bf16 v[18:21], v[126:129], v[182:185], v[18:21]
	v_mfma_f32_16x16x32_bf16 v[142:145], v[122:125], v[138:141], v[142:145]
	v_mfma_f32_16x16x32_bf16 v[146:149], v[130:133], v[138:141], v[146:149]
	v_mfma_f32_16x16x32_bf16 v[150:153], v[122:125], v[170:173], v[150:153]
	v_mfma_f32_16x16x32_bf16 v[154:157], v[130:133], v[170:173], v[154:157]
	v_mfma_f32_16x16x32_bf16 v[158:161], v[122:125], v[178:181], v[158:161]
	v_mfma_f32_16x16x32_bf16 v[162:165], v[130:133], v[178:181], v[162:165]
	v_mfma_f32_16x16x32_bf16 v[14:17], v[122:125], v[190:193], v[14:17]
	v_mfma_f32_16x16x32_bf16 v[18:21], v[130:133], v[190:193], v[18:21]
	s_setprio 0
	s_barrier
	s_add_u32 s20, s16, 0x10000
	s_addc_u32 s21, s17, 0
	s_mov_b32 m0, s38
	v_lshl_add_u64 v[118:119], s[20:21], 0, v[2:3]
	global_load_lds_dwordx4 v[118:119], off
	v_lshl_add_u64 v[118:119], s[20:21], 0, v[0:1]
	s_mov_b32 m0, s35
	s_nop 0
	global_load_lds_dwordx4 v[118:119], off
	s_waitcnt vmcnt(6)
	s_barrier
	s_setprio 1
	v_mfma_f32_16x16x32_bf16 v[22:25], v[194:197], v[134:137], v[22:25]
	v_mfma_f32_16x16x32_bf16 v[26:29], v[216:219], v[134:137], v[26:29]
	v_mfma_f32_16x16x32_bf16 v[58:61], v[194:197], v[166:169], v[58:61]
	v_mfma_f32_16x16x32_bf16 v[102:105], v[216:219], v[166:169], v[102:105]
	v_mfma_f32_16x16x32_bf16 v[106:109], v[194:197], v[174:177], v[106:109]
	v_mfma_f32_16x16x32_bf16 v[114:117], v[216:219], v[174:177], v[114:117]
	v_mfma_f32_16x16x32_bf16 v[94:97], v[194:197], v[182:185], v[94:97]
	v_mfma_f32_16x16x32_bf16 v[98:101], v[216:219], v[182:185], v[98:101]
	v_mfma_f32_16x16x32_bf16 v[22:25], v[198:201], v[138:141], v[22:25]
	v_mfma_f32_16x16x32_bf16 v[26:29], v[220:223], v[138:141], v[26:29]
	v_mfma_f32_16x16x32_bf16 v[58:61], v[198:201], v[170:173], v[58:61]
	v_mfma_f32_16x16x32_bf16 v[102:105], v[220:223], v[170:173], v[102:105]
	v_mfma_f32_16x16x32_bf16 v[106:109], v[198:201], v[178:181], v[106:109]
	v_mfma_f32_16x16x32_bf16 v[114:117], v[220:223], v[178:181], v[114:117]
	v_mfma_f32_16x16x32_bf16 v[94:97], v[198:201], v[190:193], v[94:97]
	v_mfma_f32_16x16x32_bf16 v[98:101], v[220:223], v[190:193], v[98:101]
	s_setprio 0
	s_barrier
	ds_read_b128 v[118:121], v228
	ds_read_b128 v[122:125], v228 offset:1024
	ds_read_b128 v[126:129], v228 offset:2048
	ds_read_b128 v[130:133], v228 offset:3072
	s_add_u32 s18, s18, 0x10000
	s_addc_u32 s19, s19, 0
	s_mov_b32 m0, s27
	v_lshl_add_u64 v[194:195], s[18:19], 0, v[2:3]
	ds_read_b128 v[134:137], v13 offset:32768
	ds_read_b128 v[138:141], v13 offset:33792
	ds_read_b128 v[166:169], v13 offset:34816
	ds_read_b128 v[170:173], v13 offset:35840
	ds_read_b128 v[174:177], v13 offset:36864
	ds_read_b128 v[178:181], v13 offset:37888
	ds_read_b128 v[182:185], v13 offset:38912
	ds_read_b128 v[190:193], v13 offset:39936
	global_load_lds_dwordx4 v[194:195], off
	v_lshl_add_u64 v[194:195], s[18:19], 0, v[0:1]
	s_mov_b32 m0, s28
	s_nop 0
	global_load_lds_dwordx4 v[194:195], off
	s_waitcnt lgkmcnt(8)
	s_barrier
	s_waitcnt lgkmcnt(0)
	s_setprio 1
	s_waitcnt lgkmcnt(0)
	v_mfma_f32_16x16x32_bf16 v[62:65], v[118:121], v[134:137], v[62:65]
	v_mfma_f32_16x16x32_bf16 v[66:69], v[126:129], v[134:137], v[66:69]
	v_mfma_f32_16x16x32_bf16 v[70:73], v[118:121], v[166:169], v[70:73]
	v_mfma_f32_16x16x32_bf16 v[74:77], v[126:129], v[166:169], v[74:77]
	v_mfma_f32_16x16x32_bf16 v[78:81], v[118:121], v[174:177], v[78:81]
	v_mfma_f32_16x16x32_bf16 v[82:85], v[126:129], v[174:177], v[82:85]
	v_mfma_f32_16x16x32_bf16 v[86:89], v[118:121], v[182:185], v[86:89]
	v_mfma_f32_16x16x32_bf16 v[90:93], v[126:129], v[182:185], v[90:93]
	v_mfma_f32_16x16x32_bf16 v[62:65], v[122:125], v[138:141], v[62:65]
	v_mfma_f32_16x16x32_bf16 v[66:69], v[130:133], v[138:141], v[66:69]
	v_mfma_f32_16x16x32_bf16 v[70:73], v[122:125], v[170:173], v[70:73]
	v_mfma_f32_16x16x32_bf16 v[74:77], v[130:133], v[170:173], v[74:77]
	v_mfma_f32_16x16x32_bf16 v[78:81], v[122:125], v[178:181], v[78:81]
	v_mfma_f32_16x16x32_bf16 v[82:85], v[130:133], v[178:181], v[82:85]
	v_mfma_f32_16x16x32_bf16 v[86:89], v[122:125], v[190:193], v[86:89]
	v_mfma_f32_16x16x32_bf16 v[90:93], v[130:133], v[190:193], v[90:93]
	s_setprio 0
	s_barrier
	s_mov_b32 m0, s40
	v_lshl_add_u64 v[186:187], v[186:187], 0, s[92:93]
	ds_read_b128 v[194:197], v229
	ds_read_b128 v[198:201], v229 offset:1024
	ds_read_b128 v[216:219], v229 offset:2048
	ds_read_b128 v[220:223], v229 offset:3072
	global_load_lds_dwordx4 v[186:187], off
	v_lshl_add_u64 v[186:187], v[202:203], 0, s[92:93]
	s_mov_b32 m0, s39
	s_nop 0
	global_load_lds_dwordx4 v[186:187], off
	s_barrier
	s_waitcnt lgkmcnt(0)
	s_setprio 1
	s_waitcnt lgkmcnt(0)
	v_mfma_f32_16x16x32_bf16 v[110:113], v[194:197], v[134:137], v[110:113]
	v_mfma_f32_16x16x32_bf16 v[30:33], v[216:219], v[134:137], v[30:33]
	v_mfma_f32_16x16x32_bf16 v[34:37], v[194:197], v[166:169], v[34:37]
	v_mfma_f32_16x16x32_bf16 v[38:41], v[216:219], v[166:169], v[38:41]
	v_mfma_f32_16x16x32_bf16 v[42:45], v[194:197], v[174:177], v[42:45]
	v_mfma_f32_16x16x32_bf16 v[46:49], v[216:219], v[174:177], v[46:49]
	v_mfma_f32_16x16x32_bf16 v[50:53], v[194:197], v[182:185], v[50:53]
	v_mfma_f32_16x16x32_bf16 v[54:57], v[216:219], v[182:185], v[54:57]
	v_mfma_f32_16x16x32_bf16 v[110:113], v[198:201], v[138:141], v[110:113]
	v_mfma_f32_16x16x32_bf16 v[30:33], v[220:223], v[138:141], v[30:33]
	v_mfma_f32_16x16x32_bf16 v[34:37], v[198:201], v[170:173], v[34:37]
	v_mfma_f32_16x16x32_bf16 v[38:41], v[220:223], v[170:173], v[38:41]
	v_mfma_f32_16x16x32_bf16 v[42:45], v[198:201], v[178:181], v[42:45]
	v_mfma_f32_16x16x32_bf16 v[46:49], v[220:223], v[178:181], v[46:49]
	v_mfma_f32_16x16x32_bf16 v[50:53], v[198:201], v[190:193], v[50:53]
	v_mfma_f32_16x16x32_bf16 v[54:57], v[220:223], v[190:193], v[54:57]
	s_setprio 0
	s_mov_b32 m0, s30
	v_lshl_add_u64 v[186:187], v[224:225], 0, s[92:93]
	s_barrier
	ds_read_b128 v[134:137], v13 offset:49152
	ds_read_b128 v[138:141], v13 offset:50176
	ds_read_b128 v[166:169], v13 offset:51200
	ds_read_b128 v[170:173], v13 offset:52224
	ds_read_b128 v[174:177], v13 offset:53248
	ds_read_b128 v[178:181], v13 offset:54272
	ds_read_b128 v[182:185], v13 offset:55296
	ds_read_b128 v[190:193], v13 offset:56320
	global_load_lds_dwordx4 v[186:187], off
	v_lshl_add_u64 v[186:187], v[226:227], 0, s[92:93]
	s_mov_b32 m0, s31
	s_nop 0
	global_load_lds_dwordx4 v[186:187], off
	s_barrier
	s_waitcnt lgkmcnt(0)
	s_setprio 1
	s_waitcnt lgkmcnt(0)
	v_mfma_f32_16x16x32_bf16 v[142:145], v[118:121], v[134:137], v[142:145]
	v_mfma_f32_16x16x32_bf16 v[146:149], v[126:129], v[134:137], v[146:149]
	v_mfma_f32_16x16x32_bf16 v[150:153], v[118:121], v[166:169], v[150:153]
	v_mfma_f32_16x16x32_bf16 v[154:157], v[126:129], v[166:169], v[154:157]
	v_mfma_f32_16x16x32_bf16 v[158:161], v[118:121], v[174:177], v[158:161]
	v_mfma_f32_16x16x32_bf16 v[162:165], v[126:129], v[174:177], v[162:165]
	v_mfma_f32_16x16x32_bf16 v[14:17], v[118:121], v[182:185], v[14:17]
	v_mfma_f32_16x16x32_bf16 v[18:21], v[126:129], v[182:185], v[18:21]
	v_mfma_f32_16x16x32_bf16 v[142:145], v[122:125], v[138:141], v[142:145]
	v_mfma_f32_16x16x32_bf16 v[146:149], v[130:133], v[138:141], v[146:149]
	v_mfma_f32_16x16x32_bf16 v[150:153], v[122:125], v[170:173], v[150:153]
	v_mfma_f32_16x16x32_bf16 v[154:157], v[130:133], v[170:173], v[154:157]
	v_mfma_f32_16x16x32_bf16 v[158:161], v[122:125], v[178:181], v[158:161]
	v_mfma_f32_16x16x32_bf16 v[162:165], v[130:133], v[178:181], v[162:165]
	v_mfma_f32_16x16x32_bf16 v[14:17], v[122:125], v[190:193], v[14:17]
	v_mfma_f32_16x16x32_bf16 v[18:21], v[130:133], v[190:193], v[18:21]
	s_setprio 0
	s_barrier
	s_add_u32 s16, s16, 0x10080
	s_addc_u32 s17, s17, 0
	s_mov_b32 m0, s23
	v_lshl_add_u64 v[118:119], s[16:17], 0, v[2:3]
	global_load_lds_dwordx4 v[118:119], off
	v_lshl_add_u64 v[118:119], s[16:17], 0, v[0:1]
	s_mov_b32 m0, s22
	s_nop 0
	global_load_lds_dwordx4 v[118:119], off
	s_waitcnt vmcnt(6)
	s_barrier
	s_setprio 1
	v_mfma_f32_16x16x32_bf16 v[22:25], v[194:197], v[134:137], v[22:25]
	v_mfma_f32_16x16x32_bf16 v[26:29], v[216:219], v[134:137], v[26:29]
	v_mfma_f32_16x16x32_bf16 v[58:61], v[194:197], v[166:169], v[58:61]
	v_mfma_f32_16x16x32_bf16 v[102:105], v[216:219], v[166:169], v[102:105]
	v_mfma_f32_16x16x32_bf16 v[106:109], v[194:197], v[174:177], v[106:109]
	v_mfma_f32_16x16x32_bf16 v[114:117], v[216:219], v[174:177], v[114:117]
	v_mfma_f32_16x16x32_bf16 v[94:97], v[194:197], v[182:185], v[94:97]
	v_mfma_f32_16x16x32_bf16 v[98:101], v[216:219], v[182:185], v[98:101]
	v_mfma_f32_16x16x32_bf16 v[22:25], v[198:201], v[138:141], v[22:25]
	v_mfma_f32_16x16x32_bf16 v[26:29], v[220:223], v[138:141], v[26:29]
	v_mfma_f32_16x16x32_bf16 v[58:61], v[198:201], v[170:173], v[58:61]
	v_mfma_f32_16x16x32_bf16 v[102:105], v[220:223], v[170:173], v[102:105]
	v_mfma_f32_16x16x32_bf16 v[106:109], v[198:201], v[178:181], v[106:109]
	v_mfma_f32_16x16x32_bf16 v[114:117], v[220:223], v[178:181], v[114:117]
	v_mfma_f32_16x16x32_bf16 v[94:97], v[198:201], v[190:193], v[94:97]
	v_mfma_f32_16x16x32_bf16 v[98:101], v[220:223], v[190:193], v[98:101]
	s_setprio 0
	s_lshl_b32 s7, s34, 8
	s_or_b32 s7, s7, s29
	s_ashr_i32 s16, s7, 6
	s_ashr_i32 s17, s16, 31
	s_lshl_b64 s[18:19], s[16:17], 15
	v_cvt_pk_bf16_f32 v62, v62, v63
	v_cvt_pk_bf16_f32 v63, v64, v65
	v_lshl_add_u64 v[64:65], v[4:5], 0, s[18:19]
	s_or_b32 s16, s16, 2
	v_lshl_add_u64 v[118:119], v[64:65], 0, s[2:3]
	s_ashr_i32 s17, s16, 31
	v_lshl_add_u64 v[118:119], v[118:119], 0, v[188:189]
	s_lshl_b64 s[16:17], s[16:17], 15
	s_barrier
	v_and_b32_e32 v230, 16, v204
	v_lshrrev_b32_e32 v231, 1, v230
	v_add_u32_e32 v230, v230, v231
	v_mov_b32_e32 v231, v189
	v_mov_b64_e32 v[232:233], v[62:63]
	v_cvt_pk_bf16_f32 v62, v66, v67
	v_lshl_add_u64 v[66:67], v[4:5], 0, s[16:17]
	v_cvt_pk_bf16_f32 v63, v68, v69
	v_lshl_add_u64 v[68:69], v[66:67], 0, s[2:3]
	v_mov_b64_e32 v[234:235], v[62:63]
	s_nop 1
	v_permlane16_swap_b32 v232, v234
	v_permlane16_swap_b32 v233, v235
	v_lshl_add_u64 v[248:249], v[118:119], 0, v[230:231]
	global_store_dwordx4 v[248:249], v[232:235], off
	s_nop 1
	v_cvt_pk_bf16_f32 v62, v110, v111
	v_cvt_pk_bf16_f32 v63, v112, v113
	v_lshl_add_u64 v[68:69], v[68:69], 0, v[188:189]
	v_cvt_pk_bf16_f32 v30, v30, v31
	v_cvt_pk_bf16_f32 v31, v32, v33
	v_lshl_add_u64 v[32:33], v[6:7], 0, s[18:19]
	v_mov_b64_e32 v[232:233], v[62:63]
	v_lshl_add_u64 v[62:63], v[32:33], 0, s[2:3]
	v_mov_b64_e32 v[234:235], v[30:31]
	s_nop 1
	v_permlane16_swap_b32 v232, v234
	v_permlane16_swap_b32 v233, v235
	v_lshl_add_u64 v[248:249], v[68:69], 0, v[230:231]
	global_store_dwordx4 v[248:249], v[232:235], off
	s_nop 1
	v_cvt_pk_bf16_f32 v30, v70, v71
	v_cvt_pk_bf16_f32 v31, v72, v73
	v_lshl_add_u64 v[62:63], v[62:63], 0, v[188:189]
	v_mov_b64_e32 v[232:233], v[30:31]
	v_cvt_pk_bf16_f32 v30, v74, v75
	v_cvt_pk_bf16_f32 v31, v76, v77
	v_mov_b64_e32 v[234:235], v[30:31]
	s_nop 1
	v_permlane16_swap_b32 v232, v234
	v_permlane16_swap_b32 v233, v235
	v_lshl_add_u64 v[248:249], v[62:63], 0, v[230:231]
	global_store_dwordx4 v[248:249], v[232:235], off
	s_nop 1
	v_cvt_pk_bf16_f32 v30, v34, v35
	v_lshl_add_u64 v[34:35], v[6:7], 0, s[16:17]
	v_cvt_pk_bf16_f32 v31, v36, v37
	v_lshl_add_u64 v[36:37], v[34:35], 0, s[2:3]
	v_lshl_add_u64 v[36:37], v[36:37], 0, v[188:189]
	v_mov_b64_e32 v[232:233], v[30:31]
	v_cvt_pk_bf16_f32 v30, v38, v39
	v_cvt_pk_bf16_f32 v31, v40, v41
	v_mov_b64_e32 v[234:235], v[30:31]
	s_nop 1
	v_permlane16_swap_b32 v232, v234
	v_permlane16_swap_b32 v233, v235
	v_lshl_add_u64 v[248:249], v[36:37], 0, v[230:231]
	global_store_dwordx4 v[248:249], v[232:235], off
	s_nop 1
	v_lshl_add_u64 v[36:37], v[8:9], 0, s[18:19]
	v_lshl_add_u64 v[38:39], v[36:37], 0, s[2:3]
	v_cvt_pk_bf16_f32 v30, v78, v79
	v_cvt_pk_bf16_f32 v31, v80, v81
	v_lshl_add_u64 v[38:39], v[38:39], 0, v[188:189]
	v_mov_b64_e32 v[232:233], v[30:31]
	v_cvt_pk_bf16_f32 v30, v82, v83
	v_cvt_pk_bf16_f32 v31, v84, v85
	v_mov_b64_e32 v[234:235], v[30:31]
	s_nop 1
	v_permlane16_swap_b32 v232, v234
	v_permlane16_swap_b32 v233, v235
	v_lshl_add_u64 v[248:249], v[38:39], 0, v[230:231]
	global_store_dwordx4 v[248:249], v[232:235], off
	s_nop 1
	v_lshl_add_u64 v[38:39], v[8:9], 0, s[16:17]
	v_lshl_add_u64 v[40:41], v[38:39], 0, s[2:3]
	v_cvt_pk_bf16_f32 v30, v42, v43
	v_cvt_pk_bf16_f32 v31, v44, v45
	v_lshl_add_u64 v[40:41], v[40:41], 0, v[188:189]
	v_mov_b64_e32 v[232:233], v[30:31]
	v_cvt_pk_bf16_f32 v30, v46, v47
	v_cvt_pk_bf16_f32 v31, v48, v49
	v_mov_b64_e32 v[234:235], v[30:31]
	s_nop 1
	v_permlane16_swap_b32 v232, v234
	v_permlane16_swap_b32 v233, v235
	v_lshl_add_u64 v[248:249], v[40:41], 0, v[230:231]
	global_store_dwordx4 v[248:249], v[232:235], off
	s_nop 1
	v_lshl_add_u64 v[40:41], v[10:11], 0, s[18:19]
	v_lshl_add_u64 v[42:43], v[40:41], 0, s[2:3]
	v_cvt_pk_bf16_f32 v30, v86, v87
	v_cvt_pk_bf16_f32 v31, v88, v89
	v_lshl_add_u64 v[42:43], v[42:43], 0, v[188:189]
	v_mov_b64_e32 v[232:233], v[30:31]
	v_cvt_pk_bf16_f32 v30, v90, v91
	v_cvt_pk_bf16_f32 v31, v92, v93
	v_mov_b64_e32 v[234:235], v[30:31]
	s_nop 1
	v_permlane16_swap_b32 v232, v234
	v_permlane16_swap_b32 v233, v235
	v_lshl_add_u64 v[248:249], v[42:43], 0, v[230:231]
	global_store_dwordx4 v[248:249], v[232:235], off
	s_nop 1
	v_lshl_add_u64 v[42:43], v[10:11], 0, s[16:17]
	v_lshl_add_u64 v[44:45], v[42:43], 0, s[2:3]
	v_cvt_pk_bf16_f32 v30, v50, v51
	v_cvt_pk_bf16_f32 v31, v52, v53
	v_lshl_add_u64 v[44:45], v[44:45], 0, v[188:189]
	v_cvt_pk_bf16_f32 v22, v22, v23
	v_cvt_pk_bf16_f32 v23, v24, v25
	v_lshl_add_u64 v[24:25], v[66:67], 0, s[4:5]
	v_mov_b64_e32 v[232:233], v[30:31]
	v_cvt_pk_bf16_f32 v30, v54, v55
	v_cvt_pk_bf16_f32 v31, v56, v57
	v_lshl_add_u64 v[24:25], v[24:25], 0, v[188:189]
	v_mov_b64_e32 v[234:235], v[30:31]
	s_nop 1
	v_permlane16_swap_b32 v232, v234
	v_permlane16_swap_b32 v233, v235
	v_lshl_add_u64 v[248:249], v[44:45], 0, v[230:231]
	global_store_dwordx4 v[248:249], v[232:235], off
	s_nop 1
	v_mov_b64_e32 v[232:233], v[22:23]
	v_cvt_pk_bf16_f32 v22, v26, v27
	v_cvt_pk_bf16_f32 v23, v28, v29
	v_mov_b64_e32 v[234:235], v[22:23]
	s_nop 1
	v_permlane16_swap_b32 v232, v234
	v_permlane16_swap_b32 v233, v235
	v_lshl_add_u64 v[248:249], v[24:25], 0, v[230:231]
	global_store_dwordx4 v[248:249], v[232:235], off
	s_nop 1
	v_lshl_add_u64 v[24:25], v[32:33], 0, s[4:5]
	v_cvt_pk_bf16_f32 v22, v150, v151
	v_cvt_pk_bf16_f32 v23, v152, v153
	v_lshl_add_u64 v[24:25], v[24:25], 0, v[188:189]
	v_mov_b64_e32 v[232:233], v[22:23]
	v_cvt_pk_bf16_f32 v22, v154, v155
	v_cvt_pk_bf16_f32 v23, v156, v157
	v_mov_b64_e32 v[234:235], v[22:23]
	s_nop 1
	v_permlane16_swap_b32 v232, v234
	v_permlane16_swap_b32 v233, v235
	v_lshl_add_u64 v[248:249], v[24:25], 0, v[230:231]
	global_store_dwordx4 v[248:249], v[232:235], off
	s_nop 1
	v_lshl_add_u64 v[24:25], v[34:35], 0, s[4:5]
	v_cvt_pk_bf16_f32 v22, v58, v59
	v_cvt_pk_bf16_f32 v23, v60, v61
	v_lshl_add_u64 v[24:25], v[24:25], 0, v[188:189]
	v_mov_b64_e32 v[232:233], v[22:23]
	v_cvt_pk_bf16_f32 v22, v102, v103
	v_cvt_pk_bf16_f32 v23, v104, v105
	v_mov_b64_e32 v[234:235], v[22:23]
	s_nop 1
	v_permlane16_swap_b32 v232, v234
	v_permlane16_swap_b32 v233, v235
	v_lshl_add_u64 v[248:249], v[24:25], 0, v[230:231]
	global_store_dwordx4 v[248:249], v[232:235], off
	s_nop 1
	v_lshl_add_u64 v[24:25], v[36:37], 0, s[4:5]
	v_cvt_pk_bf16_f32 v14, v14, v15
	v_cvt_pk_bf16_f32 v15, v16, v17
	v_lshl_add_u64 v[16:17], v[40:41], 0, s[4:5]
	v_cvt_pk_bf16_f32 v22, v158, v159
	v_cvt_pk_bf16_f32 v23, v160, v161
	v_lshl_add_u64 v[24:25], v[24:25], 0, v[188:189]
	v_lshl_add_u64 v[16:17], v[16:17], 0, v[188:189]
	v_mov_b64_e32 v[232:233], v[22:23]
	v_cvt_pk_bf16_f32 v22, v162, v163
	v_cvt_pk_bf16_f32 v23, v164, v165
	v_mov_b64_e32 v[236:237], v[14:15]
	v_cvt_pk_bf16_f32 v14, v18, v19
	v_cvt_pk_bf16_f32 v15, v20, v21
	v_lshl_add_u64 v[44:45], v[64:65], 0, s[4:5]
	v_mov_b64_e32 v[234:235], v[22:23]
	s_nop 1
	v_permlane16_swap_b32 v232, v234
	v_permlane16_swap_b32 v233, v235
	v_lshl_add_u64 v[248:249], v[24:25], 0, v[230:231]
	global_store_dwordx4 v[248:249], v[232:235], off
	s_nop 1
	v_lshl_add_u64 v[24:25], v[38:39], 0, s[4:5]
	v_mov_b64_e32 v[238:239], v[14:15]
	s_nop 1
	v_permlane16_swap_b32 v236, v238
	v_permlane16_swap_b32 v237, v239
	v_lshl_add_u64 v[248:249], v[16:17], 0, v[230:231]
	global_store_dwordx4 v[248:249], v[236:239], off
	s_nop 1
	v_lshl_add_u64 v[16:17], v[42:43], 0, s[4:5]
	v_cvt_pk_bf16_f32 v30, v142, v143
	v_cvt_pk_bf16_f32 v31, v144, v145
	v_lshl_add_u64 v[44:45], v[44:45], 0, v[188:189]
	v_cvt_pk_bf16_f32 v22, v106, v107
	v_cvt_pk_bf16_f32 v23, v108, v109
	v_lshl_add_u64 v[24:25], v[24:25], 0, v[188:189]
	v_cvt_pk_bf16_f32 v14, v94, v95
	v_cvt_pk_bf16_f32 v15, v96, v97
	v_lshl_add_u64 v[16:17], v[16:17], 0, v[188:189]
	v_mov_b64_e32 v[232:233], v[30:31]
	v_cvt_pk_bf16_f32 v30, v146, v147
	v_cvt_pk_bf16_f32 v31, v148, v149
	v_mov_b64_e32 v[236:237], v[22:23]
	v_cvt_pk_bf16_f32 v22, v114, v115
	v_cvt_pk_bf16_f32 v23, v116, v117
	v_mov_b64_e32 v[240:241], v[14:15]
	v_cvt_pk_bf16_f32 v14, v98, v99
	v_cvt_pk_bf16_f32 v15, v100, v101
	s_andn2_b64 vcc, exec, s[10:11]
	s_mov_b32 s34, s8
	s_mov_b64 s[22:23], s[14:15]
	s_mov_b64 s[20:21], s[12:13]
	v_mov_b64_e32 v[234:235], v[30:31]
	s_nop 1
	v_permlane16_swap_b32 v232, v234
	v_permlane16_swap_b32 v233, v235
	v_lshl_add_u64 v[248:249], v[44:45], 0, v[230:231]
	global_store_dwordx4 v[248:249], v[232:235], off
	s_nop 1
	v_mov_b64_e32 v[238:239], v[22:23]
	s_nop 1
	v_permlane16_swap_b32 v236, v238
	v_permlane16_swap_b32 v237, v239
	v_lshl_add_u64 v[248:249], v[24:25], 0, v[230:231]
	global_store_dwordx4 v[248:249], v[236:239], off
	s_nop 1
	v_mov_b64_e32 v[242:243], v[14:15]
	s_nop 1
	v_permlane16_swap_b32 v240, v242
	v_permlane16_swap_b32 v241, v243
	v_lshl_add_u64 v[248:249], v[16:17], 0, v[230:231]
	global_store_dwordx4 v[248:249], v[240:243], off
	s_nop 1
	s_cbranch_vccz .LBB0_203
